# GEMM epilogues rewritten (LDS transpose, full-line 16B stores, batched loads) for q/in-proj/out-proj; q main loop hand-written with line-sharing K-tile pairs; s_setprio 3 for SSD waves
# speedup vs baseline: 1.1566x; 1.0463x over previous
; template <bool SWAP, int MI, class AF, class BF, class EF>
; DI void gemm_tile(const AF& af, const BF& bfn, const EF& ef, int m0, int n0, int K, char* smem) {
;     ...
;   for (int kt = 0; kt < nk; ++kt) {
;     const int cur = kt & 1;
;     const u16* Ab = As + cur * AROWS * 40;
;     const u16* Bb = Bs + cur * 128 * 40;
; #pragma unroll
;     for (int ks = 0; ks < 2; ++ks) {
;       bf16x8 a[MI], b[2];
; #pragma unroll
;       for (int i = 0; i < MI; ++i) a[i] = *(const bf16x8*)&Ab[(wm * (MI * 32) + i * 32 + l32) * 40 + ks * 16 + h * 8];
; #pragma unroll
;       for (int i = 0; i < 2; ++i) b[i] = *(const bf16x8*)&Bb[(wn * 64 + i * 32 + l32) * 40 + ks * 16 + h * 8];
; #pragma unroll
;       for (int i = 0; i < MI; ++i)
; #pragma unroll
;         for (int j = 0; j < 2; ++j)
;           acc[i][j] = SWAP ? __builtin_amdgcn_mfma_f32_32x32x16_bf16(b[j], a[i], acc[i][j], 0, 0, 0)
;                            : __builtin_amdgcn_mfma_f32_32x32x16_bf16(a[i], b[j], acc[i][j], 0, 0, 0);
;     }
;     {
;       u16* An = As + (cur ^ 1) * AROWS * 40;
;       u16* Bn = Bs + (cur ^ 1) * 128 * 40;
; #pragma unroll
;       for (int i = 0; i < MI; ++i) *(u32x4*)&An[(lrow + 64 * i) * 40 + lk] = ra[i];
; #pragma unroll
;       for (int i = 0; i < 2; ++i) *(u32x4*)&Bn[(lrow + 64 * i) * 40 + lk] = rb[i];
;       const int kn = (kt + 2 < nk) ? kt + 2 : nk - 1;
;       const int k0 = kn * 32 + lk;
; #pragma unroll
;       for (int i = 0; i < MI; ++i) ra[i] = *(const u32x4*)af(m0 + lrow + 64 * i, k0);
; #pragma unroll
;       for (int i = 0; i < 2; ++i) rb[i] = *(const u32x4*)bfn(n0 + lrow + 64 * i, k0);
;     }
;     __syncthreads();
;   }
.LBB0_425:
	ds_read_b128 v[164:167], v192 offset:2560
	ds_read_b128 v[160:163], v192 offset:5120
	ds_read_b128 v[156:159], v194 offset:43520
	ds_read_b128 v[168:171], v192
	ds_read_b128 v[152:155], v192 offset:32
	ds_read_b128 v[196:199], v194 offset:40960
	ds_read_b128 v[234:237], v194 offset:40992
	s_waitcnt lgkmcnt(4)
	v_mfma_f32_32x32x16_bf16 v[64:79], v[156:159], v[164:167], v[64:79]
	s_min_u32 s1, s0, 29
	s_lshl_b32 s34, s1, 5
	v_add_lshl_u32 v172, v191, s34, 1
	s_lshl_b32 s86, s1, 6
	s_add_i32 s1, s0, 1
	s_min_u32 s1, s1, 29
	s_lshl_b32 s34, s1, 5
	s_waitcnt lgkmcnt(1)
	v_mfma_f32_32x32x16_bf16 v[80:95], v[196:199], v[164:167], v[80:95]
	s_add_i32 s0, s0, 2
	v_mfma_f32_32x32x16_bf16 v[48:63], v[196:199], v[160:163], v[48:63]
	v_mfma_f32_32x32x16_bf16 v[32:47], v[156:159], v[160:163], v[32:47]
	ds_read_b128 v[160:163], v193
	ds_read_b128 v[164:167], v193 offset:32
	v_mfma_f32_32x32x16_bf16 v[112:127], v[196:199], v[168:171], v[112:127]
	v_mfma_f32_32x32x16_bf16 v[96:111], v[156:159], v[168:171], v[96:111]
	s_waitcnt lgkmcnt(1)
	v_mfma_f32_32x32x16_bf16 v[16:31], v[196:199], v[160:163], v[16:31]
	v_mfma_f32_32x32x16_bf16 v[0:15], v[156:159], v[160:163], v[0:15]
	ds_read_b128 v[156:159], v192 offset:2592
	ds_read_b128 v[160:163], v192 offset:5152
	ds_read_b128 v[168:171], v194 offset:43552
	s_waitcnt vmcnt(3)
	ds_write_b128 v195, v[128:131] offset:20480
	s_waitcnt vmcnt(2)
	ds_write_b128 v195, v[132:135] offset:25600
	s_waitcnt vmcnt(1)
	ds_write_b128 v195, v[136:139] offset:30720
	s_waitcnt vmcnt(0)
	ds_write_b128 v195, v[140:143] offset:35840
	ds_write_b128 v195, v[144:147] offset:51200
	ds_write_b128 v195, v[148:151] offset:56320
	v_lshl_add_u64 v[128:129], v[182:183], 0, v[172:173]
	global_load_dwordx4 v[128:131], v[128:129], off
	v_lshl_add_u64 v[132:133], v[184:185], 0, v[172:173]
	global_load_dwordx4 v[132:135], v[132:133], off
	v_lshl_add_u64 v[136:137], v[186:187], 0, v[172:173]
	global_load_dwordx4 v[136:139], v[136:137], off
	v_lshl_add_u64 v[140:141], v[188:189], 0, v[172:173]
	v_lshl_add_u64 v[148:149], v[176:177], 0, s[86:87]
	global_load_dwordx4 v[140:143], v[140:141], off
	v_lshl_add_u64 v[144:145], v[148:149], 0, v[178:179]
	global_load_dwordx4 v[144:147], v[144:145], off offset:128
	v_lshl_add_u64 v[148:149], v[148:149], 0, v[180:181]
	global_load_dwordx4 v[148:151], v[148:149], off offset:128
	s_waitcnt lgkmcnt(8)
	v_mfma_f32_32x32x16_bf16 v[80:95], v[234:237], v[156:159], v[80:95]
	s_waitcnt lgkmcnt(0)
	s_barrier
	s_lshl_b32 s86, s1, 6
	v_add_lshl_u32 v172, v191, s34, 1
	s_cmp_eq_u32 s0, 32
	v_mfma_f32_32x32x16_bf16 v[64:79], v[168:171], v[156:159], v[64:79]
	v_mfma_f32_32x32x16_bf16 v[48:63], v[234:237], v[160:163], v[48:63]
	v_mfma_f32_32x32x16_bf16 v[32:47], v[168:171], v[160:163], v[32:47]
	v_mfma_f32_32x32x16_bf16 v[112:127], v[234:237], v[152:155], v[112:127]
	v_mfma_f32_32x32x16_bf16 v[96:111], v[168:171], v[152:155], v[96:111]
	v_mfma_f32_32x32x16_bf16 v[16:31], v[234:237], v[164:167], v[16:31]
	v_mfma_f32_32x32x16_bf16 v[0:15], v[168:171], v[164:167], v[0:15]
	ds_read_b128 v[152:155], v192 offset:23040
	ds_read_b128 v[156:159], v192 offset:25600
	ds_read_b128 v[160:163], v194 offset:53760
	ds_read_b128 v[164:167], v192 offset:20480
	ds_read_b128 v[168:171], v192 offset:20512
	ds_read_b128 v[196:199], v194 offset:51200
	ds_read_b128 v[234:237], v194 offset:51232
	s_waitcnt lgkmcnt(1)
	v_mfma_f32_32x32x16_bf16 v[80:95], v[196:199], v[152:155], v[80:95]
	v_mfma_f32_32x32x16_bf16 v[64:79], v[160:163], v[152:155], v[64:79]
	v_mfma_f32_32x32x16_bf16 v[48:63], v[196:199], v[156:159], v[48:63]
	v_mfma_f32_32x32x16_bf16 v[32:47], v[160:163], v[156:159], v[32:47]
	ds_read_b128 v[152:155], v193 offset:20480
	ds_read_b128 v[156:159], v193 offset:20512
	v_mfma_f32_32x32x16_bf16 v[112:127], v[196:199], v[164:167], v[112:127]
	v_mfma_f32_32x32x16_bf16 v[96:111], v[160:163], v[164:167], v[96:111]
	s_waitcnt lgkmcnt(1)
	v_mfma_f32_32x32x16_bf16 v[16:31], v[196:199], v[152:155], v[16:31]
	v_mfma_f32_32x32x16_bf16 v[0:15], v[160:163], v[152:155], v[0:15]
	ds_read_b128 v[152:155], v192 offset:23072
	ds_read_b128 v[160:163], v192 offset:25632
	ds_read_b128 v[164:167], v194 offset:53792
	s_waitcnt vmcnt(5)
	ds_write_b128 v195, v[128:131]
	s_waitcnt vmcnt(4)
	ds_write_b128 v195, v[132:135] offset:5120
	s_waitcnt vmcnt(3)
	ds_write_b128 v195, v[136:139] offset:10240
	s_waitcnt vmcnt(2)
	ds_write_b128 v195, v[140:143] offset:15360
	s_waitcnt vmcnt(1)
	ds_write_b128 v195, v[144:147] offset:40960
	s_waitcnt vmcnt(0)
	ds_write_b128 v195, v[148:151] offset:46080
	v_lshl_add_u64 v[148:149], v[176:177], 0, s[86:87]
	v_lshl_add_u64 v[128:129], v[182:183], 0, v[172:173]
	v_lshl_add_u64 v[132:133], v[184:185], 0, v[172:173]
	v_lshl_add_u64 v[136:137], v[186:187], 0, v[172:173]
	v_lshl_add_u64 v[140:141], v[188:189], 0, v[172:173]
	v_lshl_add_u64 v[144:145], v[148:149], 0, v[178:179]
	v_lshl_add_u64 v[148:149], v[148:149], 0, v[180:181]
	global_load_dwordx4 v[128:131], v[128:129], off
	v_mfma_f32_32x32x16_bf16 v[112:127], v[234:237], v[168:171], v[112:127]
	global_load_dwordx4 v[132:135], v[132:133], off
	s_nop 0
	global_load_dwordx4 v[136:139], v[136:137], off
	s_nop 0
	global_load_dwordx4 v[140:143], v[140:141], off
	s_nop 0
	global_load_dwordx4 v[144:147], v[144:145], off offset:128
	s_waitcnt lgkmcnt(6)
	v_mfma_f32_32x32x16_bf16 v[96:111], v[164:167], v[168:171], v[96:111]
	global_load_dwordx4 v[148:151], v[148:149], off offset:128
	s_waitcnt lgkmcnt(0)
	s_barrier
; DI u32 pack2(float a, float b) { return (u32)f2bf(a) | ((u32)f2bf(b) << 16); }
; template <bool SWAP, int MI, class AF, class BF, class EF>
; DI void gemm_tile(const AF& af, const BF& bfn, const EF& ef, int m0, int n0, int K, char* smem) {
;     ...
; #pragma unroll
;   for (int i = 0; i < MI; ++i)
; #pragma unroll
;     for (int j = 0; j < 2; ++j)
; #pragma unroll
;       for (int rg = 0; rg < 4; ++rg) {
;         const int m = SWAP ? (m0 + wm * (MI * 32) + i * 32 + l32) : (m0 + wm * (MI * 32) + i * 32 + rg * 8 + h * 4);
;         const int n = SWAP ? (n0 + wn * 64 + j * 32 + rg * 8 + h * 4) : (n0 + wn * 64 + j * 32 + l32);
;         ef(m, n, acc[i][j][rg * 4 + 0], acc[i][j][rg * 4 + 1], acc[i][j][rg * 4 + 2], acc[i][j][rg * 4 + 3]);
;       }
; DI void phase_inproj(const Params& p, int l, int bid, int nblk, char* smem) {
;     ...
;   auto efT = [=](int m, int n, float v0, float v1, float v2, float v3) {
;     const uint2 o = {pack2(v0, v1), pack2(v2, v3)};
;     if (n < 768) *(uint2*)&PHY[(size_t)m * 768 + n] = o;
;     else if (n < 1280) *(uint2*)&PZ[(size_t)m * 512 + (n - 768)] = o;
;     else if (n < 2304) *(uint2*)&PXBC[(size_t)m * 1024 + (n - 1280)] = o;
;     else if (n >= 2816 && n < 2832) { float4 f = {v0, v1, v2, v3}; *(float4*)&DT[(size_t)m * 16 + (n - 2816)] = f; }
	v_mfma_f32_32x32x16_bf16 v[80:95], v[234:237], v[152:155], v[80:95]
	v_mfma_f32_32x32x16_bf16 v[64:79], v[164:167], v[152:155], v[64:79]
	v_mfma_f32_32x32x16_bf16 v[48:63], v[234:237], v[160:163], v[48:63]
	v_mfma_f32_32x32x16_bf16 v[32:47], v[164:167], v[160:163], v[32:47]
	v_mfma_f32_32x32x16_bf16 v[16:31], v[234:237], v[156:159], v[16:31]
	v_mfma_f32_32x32x16_bf16 v[0:15], v[164:167], v[156:159], v[0:15]
	s_cbranch_scc0 .LBB0_425
	s_cmpk_eq_u32 s72, 0xb00
	s_cbranch_scc1 .Left_old
	s_waitcnt vmcnt(0)
	v_and_b32_e32 v128, 31, v218
	v_lshrrev_b32_e32 v129, 7, v218
	v_bfe_u32 v130, v218, 5, 1
	v_bfe_u32 v131, v218, 6, 1
	v_lshl_add_u32 v128, v129, 7, v128
	v_mul_u32_u24_e32 v128, 272, v128
	v_lshlrev_b32_e32 v131, 7, v131
	v_lshl_add_u32 v131, v130, 3, v131
	v_add_u32_e32 v128, v128, v131
	s_nop 7
	v_cvt_pk_bf16_f32 v112, v112, v113
	v_cvt_pk_bf16_f32 v113, v114, v115
	v_cvt_pk_bf16_f32 v116, v116, v117
	v_cvt_pk_bf16_f32 v117, v118, v119
	v_cvt_pk_bf16_f32 v120, v120, v121
	v_cvt_pk_bf16_f32 v121, v122, v123
	v_cvt_pk_bf16_f32 v124, v124, v125
	v_cvt_pk_bf16_f32 v125, v126, v127
	ds_write_b64 v128, v[112:113] offset:0
	ds_write_b64 v128, v[116:117] offset:16
	ds_write_b64 v128, v[120:121] offset:32
	ds_write_b64 v128, v[124:125] offset:48
	v_cvt_pk_bf16_f32 v96, v96, v97
	v_cvt_pk_bf16_f32 v97, v98, v99
	v_cvt_pk_bf16_f32 v100, v100, v101
	v_cvt_pk_bf16_f32 v101, v102, v103
	v_cvt_pk_bf16_f32 v104, v104, v105
	v_cvt_pk_bf16_f32 v105, v106, v107
	v_cvt_pk_bf16_f32 v108, v108, v109
	v_cvt_pk_bf16_f32 v109, v110, v111
	ds_write_b64 v128, v[96:97] offset:64
	ds_write_b64 v128, v[100:101] offset:80
	ds_write_b64 v128, v[104:105] offset:96
	ds_write_b64 v128, v[108:109] offset:112
	v_cvt_pk_bf16_f32 v80, v80, v81
	v_cvt_pk_bf16_f32 v81, v82, v83
	v_cvt_pk_bf16_f32 v84, v84, v85
	v_cvt_pk_bf16_f32 v85, v86, v87
	v_cvt_pk_bf16_f32 v88, v88, v89
	v_cvt_pk_bf16_f32 v89, v90, v91
	v_cvt_pk_bf16_f32 v92, v92, v93
	v_cvt_pk_bf16_f32 v93, v94, v95
	ds_write_b64 v128, v[80:81] offset:8704
	ds_write_b64 v128, v[84:85] offset:8720
	ds_write_b64 v128, v[88:89] offset:8736
	ds_write_b64 v128, v[92:93] offset:8752
	v_cvt_pk_bf16_f32 v64, v64, v65
	v_cvt_pk_bf16_f32 v65, v66, v67
	v_cvt_pk_bf16_f32 v68, v68, v69
	v_cvt_pk_bf16_f32 v69, v70, v71
	v_cvt_pk_bf16_f32 v72, v72, v73
	v_cvt_pk_bf16_f32 v73, v74, v75
	v_cvt_pk_bf16_f32 v76, v76, v77
	v_cvt_pk_bf16_f32 v77, v78, v79
	ds_write_b64 v128, v[64:65] offset:8768
	ds_write_b64 v128, v[68:69] offset:8784
	ds_write_b64 v128, v[72:73] offset:8800
	ds_write_b64 v128, v[76:77] offset:8816
	v_cvt_pk_bf16_f32 v48, v48, v49
	v_cvt_pk_bf16_f32 v49, v50, v51
	v_cvt_pk_bf16_f32 v52, v52, v53
	v_cvt_pk_bf16_f32 v53, v54, v55
	v_cvt_pk_bf16_f32 v56, v56, v57
	v_cvt_pk_bf16_f32 v57, v58, v59
	v_cvt_pk_bf16_f32 v60, v60, v61
	v_cvt_pk_bf16_f32 v61, v62, v63
	ds_write_b64 v128, v[48:49] offset:17408
	ds_write_b64 v128, v[52:53] offset:17424
	ds_write_b64 v128, v[56:57] offset:17440
	ds_write_b64 v128, v[60:61] offset:17456
	v_cvt_pk_bf16_f32 v32, v32, v33
	v_cvt_pk_bf16_f32 v33, v34, v35
	v_cvt_pk_bf16_f32 v36, v36, v37
	v_cvt_pk_bf16_f32 v37, v38, v39
	v_cvt_pk_bf16_f32 v40, v40, v41
	v_cvt_pk_bf16_f32 v41, v42, v43
	v_cvt_pk_bf16_f32 v44, v44, v45
	v_cvt_pk_bf16_f32 v45, v46, v47
	ds_write_b64 v128, v[32:33] offset:17472
	ds_write_b64 v128, v[36:37] offset:17488
	ds_write_b64 v128, v[40:41] offset:17504
	ds_write_b64 v128, v[44:45] offset:17520
	v_cvt_pk_bf16_f32 v16, v16, v17
	v_cvt_pk_bf16_f32 v17, v18, v19
	v_cvt_pk_bf16_f32 v20, v20, v21
	v_cvt_pk_bf16_f32 v21, v22, v23
	v_cvt_pk_bf16_f32 v24, v24, v25
	v_cvt_pk_bf16_f32 v25, v26, v27
	v_cvt_pk_bf16_f32 v28, v28, v29
	v_cvt_pk_bf16_f32 v29, v30, v31
	ds_write_b64 v128, v[16:17] offset:26112
	ds_write_b64 v128, v[20:21] offset:26128
	ds_write_b64 v128, v[24:25] offset:26144
	ds_write_b64 v128, v[28:29] offset:26160
	v_cvt_pk_bf16_f32 v0, v0, v1
	v_cvt_pk_bf16_f32 v1, v2, v3
	v_cvt_pk_bf16_f32 v4, v4, v5
	v_cvt_pk_bf16_f32 v5, v6, v7
	v_cvt_pk_bf16_f32 v8, v8, v9
	v_cvt_pk_bf16_f32 v9, v10, v11
	v_cvt_pk_bf16_f32 v12, v12, v13
	v_cvt_pk_bf16_f32 v13, v14, v15
	ds_write_b64 v128, v[0:1] offset:26176
	ds_write_b64 v128, v[4:5] offset:26192
	ds_write_b64 v128, v[8:9] offset:26208
	ds_write_b64 v128, v[12:13] offset:26224
	s_cmpk_lt_u32 s72, 0x300
	s_cbranch_scc1 .Left_phy
	s_cmpk_lt_u32 s72, 0x500
	s_cbranch_scc1 .Left_pz
	s_lshl_b32 s16, s73, 11
	s_lshl_b32 s17, s72, 1
	s_add_u32 s16, s16, s17
	s_add_u32 s16, s16, 0x59ff600
	s_movk_i32 s38, 0x800
	s_mov_b32 s39, 0x8000
	s_branch .Left_go
.Left_pz:
	s_lshl_b32 s16, s73, 10
	s_lshl_b32 s17, s72, 1
	s_add_u32 s16, s16, s17
	s_add_u32 s16, s16, 0x35ffa00
	s_movk_i32 s38, 0x400
	s_movk_i32 s39, 0x4000
	s_branch .Left_go
; DI u32 pack2(float a, float b) { return (u32)f2bf(a) | ((u32)f2bf(b) << 16); }
; template <bool SWAP, int MI, class AF, class BF, class EF>
; DI void gemm_tile(const AF& af, const BF& bfn, const EF& ef, int m0, int n0, int K, char* smem) {
;     ...
; #pragma unroll
;   for (int i = 0; i < MI; ++i)
; #pragma unroll
;     for (int j = 0; j < 2; ++j)
; #pragma unroll
;       for (int rg = 0; rg < 4; ++rg) {
;         const int m = SWAP ? (m0 + wm * (MI * 32) + i * 32 + l32) : (m0 + wm * (MI * 32) + i * 32 + rg * 8 + h * 4);
;         const int n = SWAP ? (n0 + wn * 64 + j * 32 + rg * 8 + h * 4) : (n0 + wn * 64 + j * 32 + l32);
;         ef(m, n, acc[i][j][rg * 4 + 0], acc[i][j][rg * 4 + 1], acc[i][j][rg * 4 + 2], acc[i][j][rg * 4 + 3]);
;       }
; DI void phase_inproj(const Params& p, int l, int bid, int nblk, char* smem) {
;     ...
;   auto efT = [=](int m, int n, float v0, float v1, float v2, float v3) {
;     const uint2 o = {pack2(v0, v1), pack2(v2, v3)};
;     if (n < 768) *(uint2*)&PHY[(size_t)m * 768 + n] = o;
;     else if (n < 1280) *(uint2*)&PZ[(size_t)m * 512 + (n - 768)] = o;
;     else if (n < 2304) *(uint2*)&PXBC[(size_t)m * 1024 + (n - 1280)] = o;
;     else if (n >= 2816 && n < 2832) { float4 f = {v0, v1, v2, v3}; *(float4*)&DT[(size_t)m * 16 + (n - 2816)] = f; }
.Left_phy:
	s_mul_i32 s16, s73, 0x600
	s_lshl_b32 s17, s72, 1
	s_add_u32 s16, s16, s17
	s_movk_i32 s38, 0x600
	s_movk_i32 s39, 0x6000
.Left_go:
	s_add_u32 s16, s96, s16
	s_addc_u32 s17, s97, 0
	v_lshrrev_b32_e32 v129, 4, v218
	v_and_b32_e32 v130, 15, v218
	v_mul_u32_u24_e32 v131, 272, v129
	v_mul_lo_u32 v132, v129, s38
	v_lshl_add_u32 v131, v130, 4, v131
	v_lshl_add_u32 v132, v130, 4, v132
	s_waitcnt lgkmcnt(0)
	s_barrier
	ds_read_b128 v[0:3], v131 offset:0
	ds_read_b128 v[4:7], v131 offset:4352
	ds_read_b128 v[8:11], v131 offset:8704
	ds_read_b128 v[12:15], v131 offset:13056
	ds_read_b128 v[16:19], v131 offset:17408
	ds_read_b128 v[20:23], v131 offset:21760
	ds_read_b128 v[24:27], v131 offset:26112
	ds_read_b128 v[28:31], v131 offset:30464
	ds_read_b128 v[32:35], v131 offset:34816
	ds_read_b128 v[36:39], v131 offset:39168
	ds_read_b128 v[40:43], v131 offset:43520
	ds_read_b128 v[44:47], v131 offset:47872
	ds_read_b128 v[48:51], v131 offset:52224
	ds_read_b128 v[52:55], v131 offset:56576
	ds_read_b128 v[56:59], v131 offset:60928
	ds_read_b128 v[60:63], v131 offset:65280
	s_waitcnt lgkmcnt(15)
	global_store_dwordx4 v132, v[0:3], s[16:17]
	s_add_u32 s16, s16, s39
	s_addc_u32 s17, s17, 0
	s_waitcnt lgkmcnt(14)
	global_store_dwordx4 v132, v[4:7], s[16:17]
	s_add_u32 s16, s16, s39
	s_addc_u32 s17, s17, 0
	s_waitcnt lgkmcnt(13)
	global_store_dwordx4 v132, v[8:11], s[16:17]
	s_add_u32 s16, s16, s39
	s_addc_u32 s17, s17, 0
	s_waitcnt lgkmcnt(12)
	global_store_dwordx4 v132, v[12:15], s[16:17]
	s_add_u32 s16, s16, s39
	s_addc_u32 s17, s17, 0
	s_waitcnt lgkmcnt(11)
	global_store_dwordx4 v132, v[16:19], s[16:17]
	s_add_u32 s16, s16, s39
	s_addc_u32 s17, s17, 0
	s_waitcnt lgkmcnt(10)
	global_store_dwordx4 v132, v[20:23], s[16:17]
	s_add_u32 s16, s16, s39
	s_addc_u32 s17, s17, 0
	s_waitcnt lgkmcnt(9)
	global_store_dwordx4 v132, v[24:27], s[16:17]
	s_add_u32 s16, s16, s39
	s_addc_u32 s17, s17, 0
	s_waitcnt lgkmcnt(8)
	global_store_dwordx4 v132, v[28:31], s[16:17]
	s_add_u32 s16, s16, s39
	s_addc_u32 s17, s17, 0
	s_waitcnt lgkmcnt(7)
	global_store_dwordx4 v132, v[32:35], s[16:17]
	s_add_u32 s16, s16, s39
	s_addc_u32 s17, s17, 0
	s_waitcnt lgkmcnt(6)
	global_store_dwordx4 v132, v[36:39], s[16:17]
	s_add_u32 s16, s16, s39
	s_addc_u32 s17, s17, 0
	s_waitcnt lgkmcnt(5)
	global_store_dwordx4 v132, v[40:43], s[16:17]
	s_add_u32 s16, s16, s39
	s_addc_u32 s17, s17, 0
	s_waitcnt lgkmcnt(4)
	global_store_dwordx4 v132, v[44:47], s[16:17]
	s_add_u32 s16, s16, s39
	s_addc_u32 s17, s17, 0
	s_waitcnt lgkmcnt(3)
	global_store_dwordx4 v132, v[48:51], s[16:17]
	s_add_u32 s16, s16, s39
	s_addc_u32 s17, s17, 0
	s_waitcnt lgkmcnt(2)
	global_store_dwordx4 v132, v[52:55], s[16:17]
	s_add_u32 s16, s16, s39
	s_addc_u32 s17, s17, 0
	s_waitcnt lgkmcnt(1)
	global_store_dwordx4 v132, v[56:59], s[16:17]
	s_add_u32 s16, s16, s39
	s_addc_u32 s17, s17, 0
	s_waitcnt lgkmcnt(0)
	global_store_dwordx4 v132, v[60:63], s[16:17]
	s_barrier
	s_branch .LBB0_416
.Left_old:
	s_waitcnt vmcnt(5)
	v_and_b32_e32 v129, 0xffffff80, v175
	v_add_u32_e32 v129, s73, v129
	v_and_b32_e32 v128, 64, v175
	v_and_or_b32 v130, v175, 31, v129
	v_lshlrev_b32_e32 v129, 2, v190
	v_or3_b32 v128, v129, v128, s72
	v_ashrrev_i32_e32 v131, 31, v130
	v_bfe_u32 v129, v112, 16, 1
	s_waitcnt vmcnt(3)
	v_lshlrev_b64 v[136:137], 6, v[130:131]
	v_lshlrev_b64 v[134:135], 11, v[130:131]
	v_lshlrev_b64 v[132:133], 10, v[130:131]
	v_add3_u32 v129, v112, v129, s76
	v_bfe_u32 v131, v113, 16, 1
	v_lshrrev_b32_e32 v129, 16, v129
	v_add3_u32 v131, v113, v131, s76
	v_and_or_b32 v138, v131, s77, v129
	v_bfe_u32 v129, v114, 16, 1
	v_add3_u32 v129, v114, v129, s76
	v_bfe_u32 v131, v115, 16, 1
	v_lshrrev_b32_e32 v129, 16, v129
	v_add3_u32 v131, v115, v131, s76
	s_movk_i32 s0, 0x2ff
	v_and_or_b32 v139, v131, s77, v129
	v_cmp_lt_i32_e64 s[0:1], s0, v128
	s_and_saveexec_b64 s[34:35], s[0:1]
	s_xor_b64 s[34:35], exec, s[34:35]
	s_cbranch_execz .LBB0_437
	s_cmpk_gt_u32 s72, 0x4ff
	s_mov_b64 s[36:37], -1
	s_cbranch_scc0 .LBB0_435
	s_cmpk_gt_u32 s72, 0x8ff
	s_cbranch_scc0 .LBB0_432
	v_and_b32_e32 v129, 0x7fffffc0, v128
	s_movk_i32 s16, 0xb00
	v_cmp_eq_u32_e32 vcc, s16, v129
	s_and_saveexec_b64 s[36:37], vcc
	s_cbranch_execz .LBB0_431
	v_readlane_b32 s16, v255, 35
	v_readlane_b32 s17, v255, 36
	v_mov_b32_e32 v129, v173
	s_waitcnt vmcnt(2)
	v_lshl_add_u64 v[140:141], s[16:17], 0, v[136:137]
	v_lshl_add_u64 v[140:141], v[128:129], 2, v[140:141]
	v_add_co_u32_e32 v140, vcc, 0xffffe000, v140
	s_nop 1
	v_addc_co_u32_e32 v141, vcc, -1, v141, vcc
	global_store_dwordx4 v[140:141], v[112:115], off offset:-3072

; template <bool SWAP, int MI, class AF, class BF, class EF>
; DI void gemm_tile(const AF& af, const BF& bfn, const EF& ef, int m0, int n0, int K, char* smem) {
;     ...
;   for (int kt = 0; kt < nk; ++kt) {
;     const int cur = kt & 1;
;     const u16* Ab = As + cur * AROWS * 40;
;     const u16* Bb = Bs + cur * 128 * 40;
; #pragma unroll
;     for (int ks = 0; ks < 2; ++ks) {
;       bf16x8 a[MI], b[2];
; #pragma unroll
;       for (int i = 0; i < MI; ++i) a[i] = *(const bf16x8*)&Ab[(wm * (MI * 32) + i * 32 + l32) * 40 + ks * 16 + h * 8];
; #pragma unroll
;       for (int i = 0; i < 2; ++i) b[i] = *(const bf16x8*)&Bb[(wn * 64 + i * 32 + l32) * 40 + ks * 16 + h * 8];
; #pragma unroll
;       for (int i = 0; i < MI; ++i)
; #pragma unroll
;         for (int j = 0; j < 2; ++j)
;           acc[i][j] = SWAP ? __builtin_amdgcn_mfma_f32_32x32x16_bf16(b[j], a[i], acc[i][j], 0, 0, 0)
;                            : __builtin_amdgcn_mfma_f32_32x32x16_bf16(a[i], b[j], acc[i][j], 0, 0, 0);
;     }
;     {
;       u16* An = As + (cur ^ 1) * AROWS * 40;
;       u16* Bn = Bs + (cur ^ 1) * 128 * 40;
; #pragma unroll
;       for (int i = 0; i < MI; ++i) *(u32x4*)&An[(lrow + 64 * i) * 40 + lk] = ra[i];
; #pragma unroll
;       for (int i = 0; i < 2; ++i) *(u32x4*)&Bn[(lrow + 64 * i) * 40 + lk] = rb[i];
;       const int kn = (kt + 2 < nk) ? kt + 2 : nk - 1;
;       const int k0 = kn * 32 + lk;
; #pragma unroll
;       for (int i = 0; i < MI; ++i) ra[i] = *(const u32x4*)af(m0 + lrow + 64 * i, k0);
; #pragma unroll
;       for (int i = 0; i < 2; ++i) rb[i] = *(const u32x4*)bfn(n0 + lrow + 64 * i, k0);
;     }
;     __syncthreads();
;   }
.LBB0_749:
	ds_read_b128 v[160:163], v185 offset:2560
	ds_read_b128 v[156:159], v185 offset:5120
	ds_read_b128 v[152:155], v187 offset:43520
	ds_read_b128 v[190:193], v185
	ds_read_b128 v[194:197], v185 offset:32
	ds_read_b128 v[198:201], v187 offset:40960
	ds_read_b128 v[234:237], v187 offset:40992
	s_waitcnt lgkmcnt(4)
	v_mfma_f32_32x32x16_bf16 v[64:79], v[160:163], v[152:155], v[64:79]
	s_min_u32 s1, s0, 29
	s_lshl_b32 s34, s1, 5
	v_add_lshl_u32 v172, v184, s34, 1
	s_lshl_b32 s86, s1, 6
	s_add_i32 s1, s0, 1
	s_min_u32 s1, s1, 29
	s_lshl_b32 s34, s1, 5
	s_waitcnt lgkmcnt(1)
	v_mfma_f32_32x32x16_bf16 v[80:95], v[160:163], v[198:201], v[80:95]
	s_add_i32 s0, s0, 2
	v_mfma_f32_32x32x16_bf16 v[48:63], v[156:159], v[198:201], v[48:63]
	v_mfma_f32_32x32x16_bf16 v[32:47], v[156:159], v[152:155], v[32:47]
	ds_read_b128 v[156:159], v186
	ds_read_b128 v[160:163], v186 offset:32
	v_mfma_f32_32x32x16_bf16 v[112:127], v[190:193], v[198:201], v[112:127]
	v_mfma_f32_32x32x16_bf16 v[96:111], v[190:193], v[152:155], v[96:111]
	s_waitcnt lgkmcnt(1)
	v_mfma_f32_32x32x16_bf16 v[16:31], v[156:159], v[198:201], v[16:31]
	v_mfma_f32_32x32x16_bf16 v[0:15], v[156:159], v[152:155], v[0:15]
	ds_read_b128 v[152:155], v185 offset:2592
	ds_read_b128 v[156:159], v185 offset:5152
	ds_read_b128 v[190:193], v187 offset:43552
	s_waitcnt vmcnt(3)
	ds_write_b128 v188, v[128:131] offset:20480
	s_waitcnt vmcnt(2)
	ds_write_b128 v188, v[132:135] offset:25600
	s_waitcnt vmcnt(1)
	ds_write_b128 v188, v[136:139] offset:30720
	s_waitcnt vmcnt(0)
	ds_write_b128 v188, v[140:143] offset:35840
	ds_write_b128 v188, v[144:147] offset:51200
	ds_write_b128 v188, v[148:151] offset:56320
	v_lshl_add_u64 v[128:129], v[170:171], 0, v[172:173]
	global_load_dwordx4 v[128:131], v[128:129], off
	v_lshl_add_u64 v[132:133], v[176:177], 0, v[172:173]
	global_load_dwordx4 v[132:135], v[132:133], off
	v_lshl_add_u64 v[136:137], v[178:179], 0, v[172:173]
	global_load_dwordx4 v[136:139], v[136:137], off
	v_lshl_add_u64 v[140:141], v[180:181], 0, v[172:173]
	v_lshl_add_u64 v[148:149], v[164:165], 0, s[86:87]
	global_load_dwordx4 v[140:143], v[140:141], off
	v_lshl_add_u64 v[144:145], v[148:149], 0, v[166:167]
	global_load_dwordx4 v[144:147], v[144:145], off offset:128
	v_lshl_add_u64 v[148:149], v[148:149], 0, v[168:169]
	global_load_dwordx4 v[148:151], v[148:149], off offset:128
	s_waitcnt lgkmcnt(8)
	v_mfma_f32_32x32x16_bf16 v[80:95], v[152:155], v[234:237], v[80:95]
	s_waitcnt lgkmcnt(0)
	s_barrier
	s_lshl_b32 s86, s1, 6
	v_add_lshl_u32 v172, v184, s34, 1
	s_cmp_lg_u32 s0, 32
	v_mfma_f32_32x32x16_bf16 v[64:79], v[152:155], v[190:193], v[64:79]
	v_mfma_f32_32x32x16_bf16 v[48:63], v[156:159], v[234:237], v[48:63]
	v_mfma_f32_32x32x16_bf16 v[32:47], v[156:159], v[190:193], v[32:47]
	v_mfma_f32_32x32x16_bf16 v[112:127], v[194:197], v[234:237], v[112:127]
	v_mfma_f32_32x32x16_bf16 v[96:111], v[194:197], v[190:193], v[96:111]
	v_mfma_f32_32x32x16_bf16 v[16:31], v[160:163], v[234:237], v[16:31]
	v_mfma_f32_32x32x16_bf16 v[0:15], v[160:163], v[190:193], v[0:15]
	ds_read_b128 v[152:155], v185 offset:23040
	ds_read_b128 v[156:159], v185 offset:25600
	ds_read_b128 v[160:163], v187 offset:53760
	ds_read_b128 v[190:193], v185 offset:20480
	ds_read_b128 v[194:197], v185 offset:20512
	ds_read_b128 v[198:201], v187 offset:51200
	ds_read_b128 v[234:237], v187 offset:51232
	s_waitcnt lgkmcnt(1)
	v_mfma_f32_32x32x16_bf16 v[80:95], v[152:155], v[198:201], v[80:95]
	v_mfma_f32_32x32x16_bf16 v[64:79], v[152:155], v[160:163], v[64:79]
	v_mfma_f32_32x32x16_bf16 v[48:63], v[156:159], v[198:201], v[48:63]
	v_mfma_f32_32x32x16_bf16 v[32:47], v[156:159], v[160:163], v[32:47]
	ds_read_b128 v[152:155], v186 offset:20480
	ds_read_b128 v[156:159], v186 offset:20512
	v_mfma_f32_32x32x16_bf16 v[112:127], v[190:193], v[198:201], v[112:127]
	v_mfma_f32_32x32x16_bf16 v[96:111], v[190:193], v[160:163], v[96:111]
	s_waitcnt lgkmcnt(1)
	v_mfma_f32_32x32x16_bf16 v[16:31], v[152:155], v[198:201], v[16:31]
	v_mfma_f32_32x32x16_bf16 v[0:15], v[152:155], v[160:163], v[0:15]
	ds_read_b128 v[152:155], v185 offset:23072
	ds_read_b128 v[160:163], v185 offset:25632
	ds_read_b128 v[190:193], v187 offset:53792
	s_waitcnt vmcnt(5)
	ds_write_b128 v188, v[128:131]
	s_waitcnt vmcnt(4)
	ds_write_b128 v188, v[132:135] offset:5120
	s_waitcnt vmcnt(3)
	ds_write_b128 v188, v[136:139] offset:10240
	s_waitcnt vmcnt(2)
	ds_write_b128 v188, v[140:143] offset:15360
	s_waitcnt vmcnt(1)
	ds_write_b128 v188, v[144:147] offset:40960
	s_waitcnt vmcnt(0)
	ds_write_b128 v188, v[148:151] offset:46080
	v_lshl_add_u64 v[148:149], v[164:165], 0, s[86:87]
	v_lshl_add_u64 v[128:129], v[170:171], 0, v[172:173]
	v_lshl_add_u64 v[132:133], v[176:177], 0, v[172:173]
	v_lshl_add_u64 v[136:137], v[178:179], 0, v[172:173]
	v_lshl_add_u64 v[140:141], v[180:181], 0, v[172:173]
	v_lshl_add_u64 v[144:145], v[148:149], 0, v[166:167]
	v_lshl_add_u64 v[148:149], v[148:149], 0, v[168:169]
	global_load_dwordx4 v[128:131], v[128:129], off
	v_mfma_f32_32x32x16_bf16 v[112:127], v[194:197], v[234:237], v[112:127]
	global_load_dwordx4 v[132:135], v[132:133], off
	s_nop 0
	global_load_dwordx4 v[136:139], v[136:137], off
	s_nop 0
	global_load_dwordx4 v[140:143], v[140:141], off
	s_nop 0
	global_load_dwordx4 v[144:147], v[144:145], off offset:128
	s_waitcnt lgkmcnt(6)
	v_mfma_f32_32x32x16_bf16 v[96:111], v[194:197], v[190:193], v[96:111]
	global_load_dwordx4 v[148:151], v[148:149], off offset:128
	s_waitcnt lgkmcnt(0)
	s_barrier
; DI u32 pack2(float a, float b) { return (u32)f2bf(a) | ((u32)f2bf(b) << 16); }
; template <bool SWAP, int MI, class AF, class BF, class EF>
; DI void gemm_tile(const AF& af, const BF& bfn, const EF& ef, int m0, int n0, int K, char* smem) {
;     ...
; #pragma unroll
;   for (int i = 0; i < MI; ++i)
; #pragma unroll
;     for (int j = 0; j < 2; ++j)
; #pragma unroll
;       for (int rg = 0; rg < 4; ++rg) {
;         const int m = SWAP ? (m0 + wm * (MI * 32) + i * 32 + l32) : (m0 + wm * (MI * 32) + i * 32 + rg * 8 + h * 4);
;         const int n = SWAP ? (n0 + wn * 64 + j * 32 + rg * 8 + h * 4) : (n0 + wn * 64 + j * 32 + l32);
;         ef(m, n, acc[i][j][rg * 4 + 0], acc[i][j][rg * 4 + 1], acc[i][j][rg * 4 + 2], acc[i][j][rg * 4 + 3]);
;       }
; DI void phase_inproj(const Params& p, int l, int bid, int nblk, char* smem) {
;     ...
;   auto efN = [=](int m, int n, float v0, float v1, float v2, float v3) {
;     const int b = m / TPB, pos = m % TPB, np = n - 2304;
;     uint2 o = {pack2(v0, v1), pack2(v2, v3)};
;     *(uint2*)&PQT[((size_t)(b * 512 + np)) * TPB + pos] = o;
;   };
	v_mfma_f32_32x32x16_bf16 v[80:95], v[152:155], v[234:237], v[80:95]
	v_mfma_f32_32x32x16_bf16 v[64:79], v[152:155], v[190:193], v[64:79]
	v_mfma_f32_32x32x16_bf16 v[48:63], v[160:163], v[234:237], v[48:63]
	v_mfma_f32_32x32x16_bf16 v[32:47], v[160:163], v[190:193], v[32:47]
	v_mfma_f32_32x32x16_bf16 v[16:31], v[156:159], v[234:237], v[16:31]
	v_mfma_f32_32x32x16_bf16 v[0:15], v[156:159], v[190:193], v[0:15]
	s_cbranch_scc1 .LBB0_749
	s_waitcnt vmcnt(0)
	v_and_b32_e32 v128, 31, v218
	v_lshrrev_b32_e32 v129, 7, v218
	v_bfe_u32 v130, v218, 5, 1
	v_bfe_u32 v131, v218, 6, 1
	v_lshl_add_u32 v128, v131, 6, v128
	v_mul_u32_u24_e32 v128, 528, v128
	v_lshlrev_b32_e32 v129, 8, v129
	v_lshl_add_u32 v129, v130, 3, v129
	v_add_u32_e32 v128, v128, v129
	s_nop 7
	v_cvt_pk_bf16_f32 v112, v112, v113
	v_cvt_pk_bf16_f32 v113, v114, v115
	v_cvt_pk_bf16_f32 v116, v116, v117
	v_cvt_pk_bf16_f32 v117, v118, v119
	v_cvt_pk_bf16_f32 v120, v120, v121
	v_cvt_pk_bf16_f32 v121, v122, v123
	v_cvt_pk_bf16_f32 v124, v124, v125
	v_cvt_pk_bf16_f32 v125, v126, v127
	ds_write_b64 v128, v[112:113] offset:0
	ds_write_b64 v128, v[116:117] offset:16
	ds_write_b64 v128, v[120:121] offset:32
	ds_write_b64 v128, v[124:125] offset:48
	v_cvt_pk_bf16_f32 v96, v96, v97
	v_cvt_pk_bf16_f32 v97, v98, v99
	v_cvt_pk_bf16_f32 v100, v100, v101
	v_cvt_pk_bf16_f32 v101, v102, v103
	v_cvt_pk_bf16_f32 v104, v104, v105
	v_cvt_pk_bf16_f32 v105, v106, v107
	v_cvt_pk_bf16_f32 v108, v108, v109
	v_cvt_pk_bf16_f32 v109, v110, v111
	ds_write_b64 v128, v[96:97] offset:16896
	ds_write_b64 v128, v[100:101] offset:16912
	ds_write_b64 v128, v[104:105] offset:16928
	ds_write_b64 v128, v[108:109] offset:16944
	v_cvt_pk_bf16_f32 v80, v80, v81
	v_cvt_pk_bf16_f32 v81, v82, v83
	v_cvt_pk_bf16_f32 v84, v84, v85
	v_cvt_pk_bf16_f32 v85, v86, v87
	v_cvt_pk_bf16_f32 v88, v88, v89
	v_cvt_pk_bf16_f32 v89, v90, v91
	v_cvt_pk_bf16_f32 v92, v92, v93
	v_cvt_pk_bf16_f32 v93, v94, v95
	ds_write_b64 v128, v[80:81] offset:64
	ds_write_b64 v128, v[84:85] offset:80
	ds_write_b64 v128, v[88:89] offset:96
	ds_write_b64 v128, v[92:93] offset:112
	v_cvt_pk_bf16_f32 v64, v64, v65
	v_cvt_pk_bf16_f32 v65, v66, v67
	v_cvt_pk_bf16_f32 v68, v68, v69
	v_cvt_pk_bf16_f32 v69, v70, v71
	v_cvt_pk_bf16_f32 v72, v72, v73
	v_cvt_pk_bf16_f32 v73, v74, v75
	v_cvt_pk_bf16_f32 v76, v76, v77
	v_cvt_pk_bf16_f32 v77, v78, v79
	ds_write_b64 v128, v[64:65] offset:16960
	ds_write_b64 v128, v[68:69] offset:16976
	ds_write_b64 v128, v[72:73] offset:16992
	ds_write_b64 v128, v[76:77] offset:17008
	v_cvt_pk_bf16_f32 v48, v48, v49
	v_cvt_pk_bf16_f32 v49, v50, v51
	v_cvt_pk_bf16_f32 v52, v52, v53
	v_cvt_pk_bf16_f32 v53, v54, v55
	v_cvt_pk_bf16_f32 v56, v56, v57
	v_cvt_pk_bf16_f32 v57, v58, v59
	v_cvt_pk_bf16_f32 v60, v60, v61
	v_cvt_pk_bf16_f32 v61, v62, v63
	ds_write_b64 v128, v[48:49] offset:128
	ds_write_b64 v128, v[52:53] offset:144
	ds_write_b64 v128, v[56:57] offset:160
	ds_write_b64 v128, v[60:61] offset:176
	v_cvt_pk_bf16_f32 v32, v32, v33
	v_cvt_pk_bf16_f32 v33, v34, v35
	v_cvt_pk_bf16_f32 v36, v36, v37
	v_cvt_pk_bf16_f32 v37, v38, v39
	v_cvt_pk_bf16_f32 v40, v40, v41
	v_cvt_pk_bf16_f32 v41, v42, v43
	v_cvt_pk_bf16_f32 v44, v44, v45
	v_cvt_pk_bf16_f32 v45, v46, v47
	ds_write_b64 v128, v[32:33] offset:17024
	ds_write_b64 v128, v[36:37] offset:17040
	ds_write_b64 v128, v[40:41] offset:17056
	ds_write_b64 v128, v[44:45] offset:17072
	v_cvt_pk_bf16_f32 v16, v16, v17
	v_cvt_pk_bf16_f32 v17, v18, v19
	v_cvt_pk_bf16_f32 v20, v20, v21
	v_cvt_pk_bf16_f32 v21, v22, v23
	v_cvt_pk_bf16_f32 v24, v24, v25
	v_cvt_pk_bf16_f32 v25, v26, v27
	v_cvt_pk_bf16_f32 v28, v28, v29
	v_cvt_pk_bf16_f32 v29, v30, v31
	ds_write_b64 v128, v[16:17] offset:192
	ds_write_b64 v128, v[20:21] offset:208
	ds_write_b64 v128, v[24:25] offset:224
	ds_write_b64 v128, v[28:29] offset:240
	v_cvt_pk_bf16_f32 v0, v0, v1
	v_cvt_pk_bf16_f32 v1, v2, v3
	v_cvt_pk_bf16_f32 v4, v4, v5
	v_cvt_pk_bf16_f32 v5, v6, v7
	v_cvt_pk_bf16_f32 v8, v8, v9
	v_cvt_pk_bf16_f32 v9, v10, v11
	v_cvt_pk_bf16_f32 v12, v12, v13
	v_cvt_pk_bf16_f32 v13, v14, v15
	ds_write_b64 v128, v[0:1] offset:17088
	ds_write_b64 v128, v[4:5] offset:17104
	ds_write_b64 v128, v[8:9] offset:17120
	ds_write_b64 v128, v[12:13] offset:17136
	s_mul_hi_u32 s36, s73, 0x38e38e39
	s_lshr_b32 s36, s36, 9
	s_mul_i32 s37, s36, 0x900
	s_sub_u32 s37, s73, s37
	s_lshl_b32 s36, s36, 9
	s_add_i32 s36, s36, s72
	s_add_i32 s36, s36, 0xfffff700
	s_mul_i32 s36, s36, 0x900
	s_add_i32 s36, s36, s37
	s_lshl_b32 s16, s36, 1
	s_add_u32 s16, s16, 0x13200000
	s_add_u32 s16, s96, s16
	s_addc_u32 s17, s97, 0
	s_movk_i32 s38, 0x1200
	s_mov_b32 s39, 0x9000
	v_lshrrev_b32_e32 v129, 5, v218
	v_and_b32_e32 v130, 31, v218
	v_mul_u32_u24_e32 v131, 528, v129
	v_mul_lo_u32 v132, v129, s38
	v_lshl_add_u32 v131, v130, 4, v131
	v_lshl_add_u32 v132, v130, 4, v132
	s_waitcnt lgkmcnt(0)
	s_barrier
; DI u32 pack2(float a, float b) { return (u32)f2bf(a) | ((u32)f2bf(b) << 16); }
; template <bool SWAP, int MI, class AF, class BF, class EF>
; DI void gemm_tile(const AF& af, const BF& bfn, const EF& ef, int m0, int n0, int K, char* smem) {
;     ...
; #pragma unroll
;   for (int i = 0; i < MI; ++i)
; #pragma unroll
;     for (int j = 0; j < 2; ++j)
; #pragma unroll
;       for (int rg = 0; rg < 4; ++rg) {
;         const int m = SWAP ? (m0 + wm * (MI * 32) + i * 32 + l32) : (m0 + wm * (MI * 32) + i * 32 + rg * 8 + h * 4);
;         const int n = SWAP ? (n0 + wn * 64 + j * 32 + rg * 8 + h * 4) : (n0 + wn * 64 + j * 32 + l32);
;         ef(m, n, acc[i][j][rg * 4 + 0], acc[i][j][rg * 4 + 1], acc[i][j][rg * 4 + 2], acc[i][j][rg * 4 + 3]);
;       }
; DI void phase_inproj(const Params& p, int l, int bid, int nblk, char* smem) {
;     ...
;   auto efN = [=](int m, int n, float v0, float v1, float v2, float v3) {
;     const int b = m / TPB, pos = m % TPB, np = n - 2304;
;     uint2 o = {pack2(v0, v1), pack2(v2, v3)};
;     *(uint2*)&PQT[((size_t)(b * 512 + np)) * TPB + pos] = o;
;   };
	ds_read_b128 v[0:3], v131 offset:0
	ds_read_b128 v[4:7], v131 offset:4224
	ds_read_b128 v[8:11], v131 offset:8448
	ds_read_b128 v[12:15], v131 offset:12672
	ds_read_b128 v[16:19], v131 offset:16896
	ds_read_b128 v[20:23], v131 offset:21120
	ds_read_b128 v[24:27], v131 offset:25344
	ds_read_b128 v[28:31], v131 offset:29568
	ds_read_b128 v[32:35], v131 offset:33792
	ds_read_b128 v[36:39], v131 offset:38016
	ds_read_b128 v[40:43], v131 offset:42240
	ds_read_b128 v[44:47], v131 offset:46464
	ds_read_b128 v[48:51], v131 offset:50688
	ds_read_b128 v[52:55], v131 offset:54912
	ds_read_b128 v[56:59], v131 offset:59136
	ds_read_b128 v[60:63], v131 offset:63360
	s_waitcnt lgkmcnt(15)
	global_store_dwordx4 v132, v[0:3], s[16:17]
	s_add_u32 s16, s16, s39
	s_addc_u32 s17, s17, 0
	s_waitcnt lgkmcnt(14)
	global_store_dwordx4 v132, v[4:7], s[16:17]
	s_add_u32 s16, s16, s39
	s_addc_u32 s17, s17, 0
	s_waitcnt lgkmcnt(13)
	global_store_dwordx4 v132, v[8:11], s[16:17]
	s_add_u32 s16, s16, s39
	s_addc_u32 s17, s17, 0
	s_waitcnt lgkmcnt(12)
	global_store_dwordx4 v132, v[12:15], s[16:17]
	s_add_u32 s16, s16, s39
	s_addc_u32 s17, s17, 0
	s_waitcnt lgkmcnt(11)
	global_store_dwordx4 v132, v[16:19], s[16:17]
	s_add_u32 s16, s16, s39
	s_addc_u32 s17, s17, 0
	s_waitcnt lgkmcnt(10)
	global_store_dwordx4 v132, v[20:23], s[16:17]
	s_add_u32 s16, s16, s39
	s_addc_u32 s17, s17, 0
	s_waitcnt lgkmcnt(9)
	global_store_dwordx4 v132, v[24:27], s[16:17]
	s_add_u32 s16, s16, s39
	s_addc_u32 s17, s17, 0
	s_waitcnt lgkmcnt(8)
	global_store_dwordx4 v132, v[28:31], s[16:17]
	s_add_u32 s16, s16, s39
	s_addc_u32 s17, s17, 0
	s_waitcnt lgkmcnt(7)
	global_store_dwordx4 v132, v[32:35], s[16:17]
	s_add_u32 s16, s16, s39
	s_addc_u32 s17, s17, 0
	s_waitcnt lgkmcnt(6)
	global_store_dwordx4 v132, v[36:39], s[16:17]
	s_add_u32 s16, s16, s39
	s_addc_u32 s17, s17, 0
	s_waitcnt lgkmcnt(5)
	global_store_dwordx4 v132, v[40:43], s[16:17]
	s_add_u32 s16, s16, s39
	s_addc_u32 s17, s17, 0
	s_waitcnt lgkmcnt(4)
	global_store_dwordx4 v132, v[44:47], s[16:17]
	s_add_u32 s16, s16, s39
	s_addc_u32 s17, s17, 0
	s_waitcnt lgkmcnt(3)
	global_store_dwordx4 v132, v[48:51], s[16:17]
	s_add_u32 s16, s16, s39
	s_addc_u32 s17, s17, 0
	s_waitcnt lgkmcnt(2)
	global_store_dwordx4 v132, v[52:55], s[16:17]
	s_add_u32 s16, s16, s39
	s_addc_u32 s17, s17, 0
	s_waitcnt lgkmcnt(1)
	global_store_dwordx4 v132, v[56:59], s[16:17]
	s_add_u32 s16, s16, s39
	s_addc_u32 s17, s17, 0
	s_waitcnt lgkmcnt(0)
	global_store_dwordx4 v132, v[60:63], s[16:17]
	s_barrier
	s_branch .LBB0_416

;   if (!(bid & 1)) for (int it = bid >> 1; it < 256; it += (nblk + 1) >> 1) ssd_item(p, l, it, smem);
.LBB0_973:
	s_or_b64 exec, exec, s[0:1]
	v_readlane_b32 s0, v255, 45
	v_readlane_b32 s1, v255, 46
	s_andn2_b64 vcc, exec, s[0:1]
	s_waitcnt lgkmcnt(0)
	s_barrier
	s_cbranch_vccnz .LBB0_1125
	s_setprio 3
	s_lshl_b32 s13, s24, 4
	v_readlane_b32 s74, v255, 44
	s_branch .LBB0_976

; DI int TID() { int t = threadIdx.x; asm volatile("" : "+v"(t)); return t; }
;   if (!(bid & 1)) for (int it = bid >> 1; it < 256; it += (nblk + 1) >> 1) ssd_item(p, l, it, smem);
;   const int nf = (l == 0) ? 288 : 256;
;   const int nh = (l == 0) ? 1280 : 1024;
;   int* ctr = WSP(int, OFF_CTR) + l + 2 * rep;
;   int* sitem = (int*)(smem + LDS_BYTES - 16);
;   for (;;) {
;     if (TID() == 0) *sitem = atomicAdd(ctr, 1);
;     __syncthreads();
;     const int it = *sitem;
;     __syncthreads();
;     if (it >= nf + nh) break;
;     if (it < nf) fnet_item(p, it, smem);
;     else if (it - nf < 1024) hyena_item_lat(p, l, it - nf);
;     else hyena_item(p, l, it - nf + 1024);
;   }
.LBB0_1125:
	s_setprio 0
	v_readlane_b32 s0, v254, 8
	v_readlane_b32 s1, v254, 9
	s_and_b64 s[0:1], s[0:1], exec
	s_movk_i32 s0, 0x120
	s_cselect_b32 s40, s0, 0x100
	s_mov_b32 s25, s87
	s_movk_i32 s0, 0x620
	s_cselect_b32 s41, s0, 0x500
	s_lshl_b32 s42, s24, 8
	s_lshl_b32 s86, s24, 13
	s_lshl_b64 s[0:1], s[24:25], 2
	v_readlane_b32 s13, v255, 48
	s_add_u32 s0, s13, s0
	v_readlane_b32 s13, v255, 49
	s_addc_u32 s1, s13, s1
	s_lshl_b64 s[34:35], s[86:87], 2
	v_readlane_b32 s16, v254, 45
	v_readlane_b32 s17, v254, 46
	s_add_u32 s43, s16, s34
	s_addc_u32 s44, s17, s35
	s_mov_b32 s64, s24
	s_branch .LBB0_1129

; template <bool SWAP, int MI, class AF, class BF, class EF>
; DI void gemm_tile(const AF& af, const BF& bfn, const EF& ef, int m0, int n0, int K, char* smem) {
;     ...
;   for (int kt = 0; kt < nk; ++kt) {
;     const int cur = kt & 1;
;     const u16* Ab = As + cur * AROWS * 40;
;     const u16* Bb = Bs + cur * 128 * 40;
; #pragma unroll
;     for (int ks = 0; ks < 2; ++ks) {
;       bf16x8 a[MI], b[2];
; #pragma unroll
;       for (int i = 0; i < MI; ++i) a[i] = *(const bf16x8*)&Ab[(wm * (MI * 32) + i * 32 + l32) * 40 + ks * 16 + h * 8];
; #pragma unroll
;       for (int i = 0; i < 2; ++i) b[i] = *(const bf16x8*)&Bb[(wn * 64 + i * 32 + l32) * 40 + ks * 16 + h * 8];
; #pragma unroll
;       for (int i = 0; i < MI; ++i)
; #pragma unroll
;         for (int j = 0; j < 2; ++j)
;           acc[i][j] = SWAP ? __builtin_amdgcn_mfma_f32_32x32x16_bf16(b[j], a[i], acc[i][j], 0, 0, 0)
;                            : __builtin_amdgcn_mfma_f32_32x32x16_bf16(a[i], b[j], acc[i][j], 0, 0, 0);
;     }
;     {
;       u16* An = As + (cur ^ 1) * AROWS * 40;
;       u16* Bn = Bs + (cur ^ 1) * 128 * 40;
; #pragma unroll
;       for (int i = 0; i < MI; ++i) *(u32x4*)&An[(lrow + 64 * i) * 40 + lk] = ra[i];
; #pragma unroll
;       for (int i = 0; i < 2; ++i) *(u32x4*)&Bn[(lrow + 64 * i) * 40 + lk] = rb[i];
;       const int kn = (kt + 2 < nk) ? kt + 2 : nk - 1;
;       const int k0 = kn * 32 + lk;
; #pragma unroll
;       for (int i = 0; i < MI; ++i) ra[i] = *(const u32x4*)af(m0 + lrow + 64 * i, k0);
; #pragma unroll
;       for (int i = 0; i < 2; ++i) rb[i] = *(const u32x4*)bfn(n0 + lrow + 64 * i, k0);
;     }
;     __syncthreads();
;   }
; DI void phase_outproj(const Params& p, int l, int bid, int nblk, char* smem) {
;     ...
;   auto ef = [=](int m, int n, float v0, float v1, float v2, float v3) {
;     const int b = m / TPB, pos = m % TPB;
;     const float4 ga = *(const float4*)&MOD[(size_t)(l * 17 + (pos < CTXL ? 16 : b)) * 6144 + 2048 + n];
;     const float4 xo = *(const float4*)(xrow_ptr(pp, l == 0, b, pos) + n);
;     const float4 o = {xo.x + ga.x * v0, xo.y + ga.y * v1, xo.z + ga.z * v2, xo.w + ga.w * v3};
;     *(float4*)(xrow_wptr(pp, b, pos) + n) = o;
.LBB0_1266:
	ds_read_b128 v[98:101], v97 offset:2560
	ds_read_b128 v[102:105], v95 offset:23040
	ds_read_b128 v[106:109], v97
	ds_read_b128 v[110:113], v97 offset:32
	ds_read_b128 v[114:117], v95 offset:20480
	ds_read_b128 v[118:121], v95 offset:20512
	s_min_u32 s44, s43, 29
	s_lshl_b32 s45, s44, 5
	v_add_lshl_u32 v172, v94, s45, 1
	s_waitcnt lgkmcnt(3)
	v_mfma_f32_32x32x16_bf16 v[32:47], v[102:105], v[106:109], v[32:47]
	s_lshl_b32 s86, s44, 6
	s_add_i32 s44, s43, 1
	s_min_u32 s44, s44, 29
	s_lshl_b32 s45, s44, 5
	s_add_i32 s43, s43, 2
	s_waitcnt lgkmcnt(1)
	v_mfma_f32_32x32x16_bf16 v[16:31], v[114:117], v[98:101], v[16:31]
	v_mfma_f32_32x32x16_bf16 v[0:15], v[102:105], v[98:101], v[0:15]
	ds_read_b128 v[98:101], v97 offset:2592
	ds_read_b128 v[102:105], v95 offset:23072
	s_waitcnt vmcnt(1)
	ds_write_b128 v96, v[64:67] offset:10240
	s_waitcnt vmcnt(0)
	ds_write_b128 v96, v[68:71] offset:15360
	ds_write_b128 v96, v[72:75] offset:30720
	ds_write_b128 v96, v[76:79] offset:35840
	v_lshl_add_u64 v[64:65], v[86:87], 0, v[172:173]
	global_load_dwordx4 v[64:67], v[64:65], off
	v_lshl_add_u64 v[68:69], v[88:89], 0, v[172:173]
	v_lshl_add_u64 v[76:77], v[80:81], 0, s[86:87]
	global_load_dwordx4 v[68:71], v[68:69], off
	v_lshl_add_u64 v[72:73], v[76:77], 0, v[82:83]
	global_load_dwordx4 v[72:75], v[72:73], off offset:128
	v_lshl_add_u64 v[76:77], v[76:77], 0, v[84:85]
	global_load_dwordx4 v[76:79], v[76:77], off offset:128
	v_mfma_f32_32x32x16_bf16 v[48:63], v[114:117], v[106:109], v[48:63]
	s_waitcnt lgkmcnt(0)
	s_barrier
	s_lshl_b32 s86, s44, 6
	v_add_lshl_u32 v172, v94, s45, 1
	s_cmp_eq_u32 s43, 32
	v_mfma_f32_32x32x16_bf16 v[32:47], v[102:105], v[110:113], v[32:47]
	v_mfma_f32_32x32x16_bf16 v[16:31], v[118:121], v[98:101], v[16:31]
	v_mfma_f32_32x32x16_bf16 v[0:15], v[102:105], v[98:101], v[0:15]
	v_mfma_f32_32x32x16_bf16 v[48:63], v[118:121], v[110:113], v[48:63]
	ds_read_b128 v[98:101], v97 offset:12800
	ds_read_b128 v[102:105], v95 offset:33280
	ds_read_b128 v[106:109], v97 offset:10240
	ds_read_b128 v[110:113], v97 offset:10272
	ds_read_b128 v[114:117], v95 offset:30720
	ds_read_b128 v[118:121], v95 offset:30752
	s_waitcnt lgkmcnt(3)
	v_mfma_f32_32x32x16_bf16 v[32:47], v[102:105], v[106:109], v[32:47]
	s_waitcnt lgkmcnt(1)
	v_mfma_f32_32x32x16_bf16 v[16:31], v[114:117], v[98:101], v[16:31]
	v_mfma_f32_32x32x16_bf16 v[0:15], v[102:105], v[98:101], v[0:15]
	ds_read_b128 v[98:101], v97 offset:12832
	ds_read_b128 v[102:105], v95 offset:33312
	s_waitcnt vmcnt(3)
	ds_write_b128 v96, v[64:67]
	s_waitcnt vmcnt(2)
	ds_write_b128 v96, v[68:71] offset:5120
	s_waitcnt vmcnt(1)
	ds_write_b128 v96, v[72:75] offset:20480
	s_waitcnt vmcnt(0)
	ds_write_b128 v96, v[76:79] offset:25600
	v_lshl_add_u64 v[76:77], v[80:81], 0, s[86:87]
	v_lshl_add_u64 v[64:65], v[86:87], 0, v[172:173]
	v_lshl_add_u64 v[68:69], v[88:89], 0, v[172:173]
	v_lshl_add_u64 v[72:73], v[76:77], 0, v[82:83]
	v_lshl_add_u64 v[76:77], v[76:77], 0, v[84:85]
	global_load_dwordx4 v[64:67], v[64:65], off
	v_mfma_f32_32x32x16_bf16 v[48:63], v[114:117], v[106:109], v[48:63]
	global_load_dwordx4 v[68:71], v[68:69], off
	s_nop 0
	global_load_dwordx4 v[72:75], v[72:73], off offset:128
	s_nop 0
	global_load_dwordx4 v[76:79], v[76:77], off offset:128
	s_waitcnt lgkmcnt(0)
	s_barrier
	v_mfma_f32_32x32x16_bf16 v[48:63], v[118:121], v[110:113], v[48:63]
	v_mfma_f32_32x32x16_bf16 v[32:47], v[102:105], v[110:113], v[32:47]
	v_mfma_f32_32x32x16_bf16 v[16:31], v[118:121], v[98:101], v[16:31]
	v_mfma_f32_32x32x16_bf16 v[0:15], v[102:105], v[98:101], v[0:15]
	s_cbranch_scc0 .LBB0_1266
	s_waitcnt vmcnt(0)
	s_mul_hi_u32 s16, s42, 0x38e38e39
	s_lshr_b32 s16, s16, 9
	s_mul_i32 s17, s16, 0x900
	s_sub_u32 s17, s42, s17
	s_cmp_lt_u32 s17, 0x100
	s_cbranch_scc1 .Lop_ctx
	s_lshl_b32 s18, s16, 11
	s_add_i32 s18, s18, s17
	s_add_i32 s18, s18, 0xffffff00
	s_lshl_b32 s18, s18, 12
	s_add_u32 s48, s38, s18
	s_addc_u32 s49, s39, 0
	s_add_u32 s50, s94, s18
	s_addc_u32 s51, s95, 0
	s_add_i32 s19, s16, s11
	s_branch .Lop_go
.Lop_ctx:
	s_lshl_b32 s18, s16, 8
	s_add_i32 s18, s18, s17
	s_lshl_b32 s18, s18, 12
	s_add_u32 s48, s40, s18
	s_addc_u32 s49, s41, 0
	v_readlane_b32 s50, v253, 21
	v_readlane_b32 s51, v253, 22
	s_add_u32 s50, s50, s18
	s_addc_u32 s51, s51, 0
	s_add_i32 s19, s11, 16
; DI const float* xrow_ptr(const Params& p, bool from_input, int b, int pos) {
;   if (pos < CTXL) return (from_input ? p.in[I_CTX] : WSP(const float, OFF_XC)) + ((size_t)b * CTXL + pos) * D;
;   return (from_input ? p.in[I_X] : (const float*)p.out) + ((size_t)b * SEQ + (pos - CTXL)) * D;
; }
; DI float* xrow_wptr(const Params& p, int b, int pos) {
;   if (pos < CTXL) return WSP(float, OFF_XC) + ((size_t)b * CTXL + pos) * D;
;   return p.out + ((size_t)b * SEQ + (pos - CTXL)) * D;
; }
; DI void phase_outproj(const Params& p, int l, int bid, int nblk, char* smem) {
;     ...
;   auto ef = [=](int m, int n, float v0, float v1, float v2, float v3) {
;     const int b = m / TPB, pos = m % TPB;
;     const float4 ga = *(const float4*)&MOD[(size_t)(l * 17 + (pos < CTXL ? 16 : b)) * 6144 + 2048 + n];
;     const float4 xo = *(const float4*)(xrow_ptr(pp, l == 0, b, pos) + n);
;     const float4 o = {xo.x + ga.x * v0, xo.y + ga.y * v1, xo.z + ga.z * v2, xo.w + ga.w * v3};
;     *(float4*)(xrow_wptr(pp, b, pos) + n) = o;
.Lop_go:
	s_lshl_b32 s18, s35, 2
	s_add_u32 s48, s48, s18
	s_addc_u32 s49, s49, 0
	s_add_u32 s50, s50, s18
	s_addc_u32 s51, s51, 0
	s_mul_i32 s19, s19, 0x6000
	v_readlane_b32 s20, v253, 19
	v_readlane_b32 s21, v253, 20
	s_add_u32 s20, s20, s19
	s_addc_u32 s21, s21, 0
	s_add_u32 s20, s20, s18
	s_addc_u32 s21, s21, 0
	s_add_u32 s20, s20, 0x2000
	s_addc_u32 s21, s21, 0
	v_and_b32_e32 v128, 31, v218
	v_lshrrev_b32_e32 v129, 7, v218
	v_bfe_u32 v130, v218, 5, 1
	v_bfe_u32 v131, v218, 6, 1
	v_lshl_add_u32 v128, v129, 6, v128
	v_mul_u32_u24_e32 v128, 528, v128
	v_lshlrev_b32_e32 v131, 8, v131
	v_lshl_add_u32 v131, v130, 4, v131
	v_add_u32_e32 v128, v128, v131
	v_lshrrev_b32_e32 v129, 5, v218
	v_and_b32_e32 v130, 31, v218
	v_lshlrev_b32_e32 v132, 12, v129
	v_lshlrev_b32_e32 v133, 4, v130
	v_lshl_add_u32 v132, v130, 4, v132
	global_load_dwordx4 v[136:139], v133, s[20:21]
	global_load_dwordx4 v[64:67], v132, s[48:49]
	s_add_u32 s48, s48, 0x8000
	s_addc_u32 s49, s49, 0
	global_load_dwordx4 v[68:71], v132, s[48:49]
	s_add_u32 s48, s48, 0x8000
	s_addc_u32 s49, s49, 0
	global_load_dwordx4 v[72:75], v132, s[48:49]
	s_add_u32 s48, s48, 0x8000
	s_addc_u32 s49, s49, 0
	global_load_dwordx4 v[76:79], v132, s[48:49]
	s_add_u32 s48, s48, 0x8000
	s_addc_u32 s49, s49, 0
	global_load_dwordx4 v[80:83], v132, s[48:49]
	s_add_u32 s48, s48, 0x8000
	s_addc_u32 s49, s49, 0
	global_load_dwordx4 v[84:87], v132, s[48:49]
	s_add_u32 s48, s48, 0x8000
	s_addc_u32 s49, s49, 0
	global_load_dwordx4 v[88:91], v132, s[48:49]
	s_add_u32 s48, s48, 0x8000
	s_addc_u32 s49, s49, 0
	global_load_dwordx4 v[92:95], v132, s[48:49]
	s_add_u32 s48, s48, 0x8000
	s_addc_u32 s49, s49, 0
	global_load_dwordx4 v[96:99], v132, s[48:49]
	s_add_u32 s48, s48, 0x8000
	s_addc_u32 s49, s49, 0
	global_load_dwordx4 v[100:103], v132, s[48:49]
	s_add_u32 s48, s48, 0x8000
	s_addc_u32 s49, s49, 0
	global_load_dwordx4 v[104:107], v132, s[48:49]
	s_add_u32 s48, s48, 0x8000
	s_addc_u32 s49, s49, 0
	global_load_dwordx4 v[108:111], v132, s[48:49]
	s_add_u32 s48, s48, 0x8000
	s_addc_u32 s49, s49, 0
	global_load_dwordx4 v[112:115], v132, s[48:49]
	s_add_u32 s48, s48, 0x8000
	s_addc_u32 s49, s49, 0
	global_load_dwordx4 v[116:119], v132, s[48:49]
	s_add_u32 s48, s48, 0x8000
	s_addc_u32 s49, s49, 0
	global_load_dwordx4 v[120:123], v132, s[48:49]
	s_add_u32 s48, s48, 0x8000
	s_addc_u32 s49, s49, 0
	global_load_dwordx4 v[124:127], v132, s[48:49]
	ds_write_b128 v128, v[48:51] offset:0
	ds_write_b128 v128, v[52:55] offset:32
	ds_write_b128 v128, v[56:59] offset:64
	ds_write_b128 v128, v[60:63] offset:96
	ds_write_b128 v128, v[32:35] offset:128
	ds_write_b128 v128, v[36:39] offset:160
	ds_write_b128 v128, v[40:43] offset:192
	ds_write_b128 v128, v[44:47] offset:224
	ds_write_b128 v128, v[16:19] offset:16896
	ds_write_b128 v128, v[20:23] offset:16928
	ds_write_b128 v128, v[24:27] offset:16960
	ds_write_b128 v128, v[28:31] offset:16992
	ds_write_b128 v128, v[0:3] offset:17024
	ds_write_b128 v128, v[4:7] offset:17056
	ds_write_b128 v128, v[8:11] offset:17088
	ds_write_b128 v128, v[12:15] offset:17120
	v_mul_u32_u24_e32 v131, 528, v129
	v_lshl_add_u32 v131, v130, 4, v131
	s_waitcnt lgkmcnt(0)
	s_barrier
; template <bool SWAP, int MI, class AF, class BF, class EF>
; DI void gemm_tile(const AF& af, const BF& bfn, const EF& ef, int m0, int n0, int K, char* smem) {
;     ...
; #pragma unroll
;   for (int i = 0; i < MI; ++i)
; #pragma unroll
;     for (int j = 0; j < 2; ++j)
; #pragma unroll
;       for (int rg = 0; rg < 4; ++rg) {
;         const int m = SWAP ? (m0 + wm * (MI * 32) + i * 32 + l32) : (m0 + wm * (MI * 32) + i * 32 + rg * 8 + h * 4);
;         const int n = SWAP ? (n0 + wn * 64 + j * 32 + rg * 8 + h * 4) : (n0 + wn * 64 + j * 32 + l32);
;         ef(m, n, acc[i][j][rg * 4 + 0], acc[i][j][rg * 4 + 1], acc[i][j][rg * 4 + 2], acc[i][j][rg * 4 + 3]);
;       }
; DI void phase_outproj(const Params& p, int l, int bid, int nblk, char* smem) {
;     ...
;   auto ef = [=](int m, int n, float v0, float v1, float v2, float v3) {
;     const int b = m / TPB, pos = m % TPB;
;     const float4 ga = *(const float4*)&MOD[(size_t)(l * 17 + (pos < CTXL ? 16 : b)) * 6144 + 2048 + n];
;     const float4 xo = *(const float4*)(xrow_ptr(pp, l == 0, b, pos) + n);
;     const float4 o = {xo.x + ga.x * v0, xo.y + ga.y * v1, xo.z + ga.z * v2, xo.w + ga.w * v3};
;     *(float4*)(xrow_wptr(pp, b, pos) + n) = o;
	ds_read_b128 v[0:3], v131 offset:0
	ds_read_b128 v[4:7], v131 offset:4224
	ds_read_b128 v[8:11], v131 offset:8448
	ds_read_b128 v[12:15], v131 offset:12672
	ds_read_b128 v[16:19], v131 offset:16896
	ds_read_b128 v[20:23], v131 offset:21120
	ds_read_b128 v[24:27], v131 offset:25344
	ds_read_b128 v[28:31], v131 offset:29568
	ds_read_b128 v[32:35], v131 offset:33792
	ds_read_b128 v[36:39], v131 offset:38016
	ds_read_b128 v[40:43], v131 offset:42240
	ds_read_b128 v[44:47], v131 offset:46464
	ds_read_b128 v[48:51], v131 offset:50688
	ds_read_b128 v[52:55], v131 offset:54912
	ds_read_b128 v[56:59], v131 offset:59136
	ds_read_b128 v[60:63], v131 offset:63360
	s_waitcnt vmcnt(15) lgkmcnt(15)
	v_pk_fma_f32 v[0:1], v[136:137], v[0:1], v[64:65]
	v_pk_fma_f32 v[2:3], v[138:139], v[2:3], v[66:67]
	s_nop 0
	global_store_dwordx4 v132, v[0:3], s[50:51]
	s_add_u32 s50, s50, 0x8000
	s_addc_u32 s51, s51, 0
	s_waitcnt vmcnt(15) lgkmcnt(14)
	v_pk_fma_f32 v[4:5], v[136:137], v[4:5], v[68:69]
	v_pk_fma_f32 v[6:7], v[138:139], v[6:7], v[70:71]
	s_nop 0
	global_store_dwordx4 v132, v[4:7], s[50:51]
	s_add_u32 s50, s50, 0x8000
	s_addc_u32 s51, s51, 0
	s_waitcnt vmcnt(15) lgkmcnt(13)
	v_pk_fma_f32 v[8:9], v[136:137], v[8:9], v[72:73]
	v_pk_fma_f32 v[10:11], v[138:139], v[10:11], v[74:75]
	s_nop 0
	global_store_dwordx4 v132, v[8:11], s[50:51]
	s_add_u32 s50, s50, 0x8000
	s_addc_u32 s51, s51, 0
	s_waitcnt vmcnt(15) lgkmcnt(12)
	v_pk_fma_f32 v[12:13], v[136:137], v[12:13], v[76:77]
	v_pk_fma_f32 v[14:15], v[138:139], v[14:15], v[78:79]
	s_nop 0
	global_store_dwordx4 v132, v[12:15], s[50:51]
	s_add_u32 s50, s50, 0x8000
	s_addc_u32 s51, s51, 0
	s_waitcnt vmcnt(15) lgkmcnt(11)
	v_pk_fma_f32 v[16:17], v[136:137], v[16:17], v[80:81]
	v_pk_fma_f32 v[18:19], v[138:139], v[18:19], v[82:83]
	s_nop 0
	global_store_dwordx4 v132, v[16:19], s[50:51]
	s_add_u32 s50, s50, 0x8000
	s_addc_u32 s51, s51, 0
	s_waitcnt vmcnt(15) lgkmcnt(10)
	v_pk_fma_f32 v[20:21], v[136:137], v[20:21], v[84:85]
	v_pk_fma_f32 v[22:23], v[138:139], v[22:23], v[86:87]
	s_nop 0
	global_store_dwordx4 v132, v[20:23], s[50:51]
	s_add_u32 s50, s50, 0x8000
	s_addc_u32 s51, s51, 0
	s_waitcnt vmcnt(15) lgkmcnt(9)
	v_pk_fma_f32 v[24:25], v[136:137], v[24:25], v[88:89]
	v_pk_fma_f32 v[26:27], v[138:139], v[26:27], v[90:91]
	s_nop 0
	global_store_dwordx4 v132, v[24:27], s[50:51]
	s_add_u32 s50, s50, 0x8000
	s_addc_u32 s51, s51, 0
	s_waitcnt vmcnt(15) lgkmcnt(8)
	v_pk_fma_f32 v[28:29], v[136:137], v[28:29], v[92:93]
	v_pk_fma_f32 v[30:31], v[138:139], v[30:31], v[94:95]
	s_nop 0
	global_store_dwordx4 v132, v[28:31], s[50:51]
	s_add_u32 s50, s50, 0x8000
	s_addc_u32 s51, s51, 0
	s_waitcnt vmcnt(15) lgkmcnt(7)
	v_pk_fma_f32 v[32:33], v[136:137], v[32:33], v[96:97]
	v_pk_fma_f32 v[34:35], v[138:139], v[34:35], v[98:99]
	s_nop 0
	global_store_dwordx4 v132, v[32:35], s[50:51]
	s_add_u32 s50, s50, 0x8000
	s_addc_u32 s51, s51, 0
	s_waitcnt vmcnt(15) lgkmcnt(6)
	v_pk_fma_f32 v[36:37], v[136:137], v[36:37], v[100:101]
	v_pk_fma_f32 v[38:39], v[138:139], v[38:39], v[102:103]
	s_nop 0
	global_store_dwordx4 v132, v[36:39], s[50:51]
	s_add_u32 s50, s50, 0x8000
	s_addc_u32 s51, s51, 0
	s_waitcnt vmcnt(15) lgkmcnt(5)
	v_pk_fma_f32 v[40:41], v[136:137], v[40:41], v[104:105]
	v_pk_fma_f32 v[42:43], v[138:139], v[42:43], v[106:107]
	s_nop 0
	global_store_dwordx4 v132, v[40:43], s[50:51]
	s_add_u32 s50, s50, 0x8000
	s_addc_u32 s51, s51, 0
	s_waitcnt vmcnt(15) lgkmcnt(4)
	v_pk_fma_f32 v[44:45], v[136:137], v[44:45], v[108:109]
	v_pk_fma_f32 v[46:47], v[138:139], v[46:47], v[110:111]
	s_nop 0
	global_store_dwordx4 v132, v[44:47], s[50:51]
	s_add_u32 s50, s50, 0x8000
	s_addc_u32 s51, s51, 0
	s_waitcnt vmcnt(15) lgkmcnt(3)
	v_pk_fma_f32 v[48:49], v[136:137], v[48:49], v[112:113]
	v_pk_fma_f32 v[50:51], v[138:139], v[50:51], v[114:115]
	s_nop 0
	global_store_dwordx4 v132, v[48:51], s[50:51]
	s_add_u32 s50, s50, 0x8000
	s_addc_u32 s51, s51, 0
	s_waitcnt vmcnt(15) lgkmcnt(2)
	v_pk_fma_f32 v[52:53], v[136:137], v[52:53], v[116:117]
	v_pk_fma_f32 v[54:55], v[138:139], v[54:55], v[118:119]
	s_nop 0
	global_store_dwordx4 v132, v[52:55], s[50:51]
	s_add_u32 s50, s50, 0x8000
	s_addc_u32 s51, s51, 0
	s_waitcnt vmcnt(15) lgkmcnt(1)
	v_pk_fma_f32 v[56:57], v[136:137], v[56:57], v[120:121]
	v_pk_fma_f32 v[58:59], v[138:139], v[58:59], v[122:123]
	s_nop 0
	global_store_dwordx4 v132, v[56:59], s[50:51]
	s_add_u32 s50, s50, 0x8000
	s_addc_u32 s51, s51, 0
	s_waitcnt vmcnt(15) lgkmcnt(0)
	v_pk_fma_f32 v[60:61], v[136:137], v[60:61], v[124:125]
	v_pk_fma_f32 v[62:63], v[138:139], v[62:63], v[126:127]
	s_nop 0
	global_store_dwordx4 v132, v[60:63], s[50:51]
	s_barrier
	s_add_i32 s34, s34, s54
	s_cmp_ge_i32 s34, s13
	s_cbranch_scc0 .LBB0_1262
	v_readlane_b32 s18, v254, 10
	s_mov_b64 s[20:21], s[46:47]
	s_mov_b32 s24, s64
	v_readlane_b32 s19, v254, 11

; DI int TID() { int t = threadIdx.x; asm volatile("" : "+v"(t)); return t; }
; template <bool SWAP, int MI, class AF, class BF, class EF>
; DI void gemm_tile(const AF& af, const BF& bfn, const EF& ef, int m0, int n0, int K, char* smem) {
;   constexpr int AROWS = MI * 64;
;   u16* As = (u16*)smem;
;   u16* Bs = As + 2 * AROWS * 40;
;   const int tid = TID(), lane = tid & 63, w = tid >> 6;
;   const int wm = w >> 1, wn = w & 1, l32 = lane & 31, h = lane >> 5;
;   const int lrow = (tid >> 6) * 16 + ((tid >> 5) & 1) * 8 + ((tid >> 2) & 1) * 4 + ((tid >> 3) & 3), lk = (tid & 3) * 8;
;   f32x16 acc[MI][2];
; #pragma unroll
;   for (int i = 0; i < MI; ++i)
; #pragma unroll
;     for (int j = 0; j < 2; ++j)
; #pragma unroll
;       for (int r = 0; r < 16; ++r) acc[i][j][r] = 0.f;
;   u32x4 ra[MI], rb[2];
;   const int nk = K >> 5;
; #pragma unroll
;   for (int i = 0; i < MI; ++i) ra[i] = *(const u32x4*)af(m0 + lrow + 64 * i, lk);
; #pragma unroll
;   for (int i = 0; i < 2; ++i) rb[i] = *(const u32x4*)bfn(n0 + lrow + 64 * i, lk);
; #pragma unroll
;   for (int i = 0; i < MI; ++i) *(u32x4*)&As[(lrow + 64 * i) * 40 + lk] = ra[i];
; #pragma unroll
;   for (int i = 0; i < 2; ++i) *(u32x4*)&Bs[(lrow + 64 * i) * 40 + lk] = rb[i];
;   {
;     const int k1 = (nk > 1) ? 32 + lk : lk;
; #pragma unroll
;     for (int i = 0; i < MI; ++i) ra[i] = *(const u32x4*)af(m0 + lrow + 64 * i, k1);
; #pragma unroll
;     for (int i = 0; i < 2; ++i) rb[i] = *(const u32x4*)bfn(n0 + lrow + 64 * i, k1);
;   }
;   __syncthreads();
; DI void phase_q(const Params& p, int l, int bid, int nblk, char* smem) {
;     ...
;   const int ntile = (l == 1 ? NB * 8 : ROWS / 256) * 16;
;   const int vb = (nblk % 8 == 0) ? (bid & 7) * (nblk >> 3) + (bid >> 3) : bid;
;   for (int t = vb; t < ntile; t += nblk) {
;     const int mi = t >> 4, nt = t & 15;
;     const int mt = (l == 1) ? (mi >> 3) * 9 + (mi & 7) + 1 : mi;
;     gemm_tile<true, 4>(af, bfn, ef, mt * 256, nt * 128, 1024, smem);
.LBB0_1390:
	s_lshl_b32 s78, s35, 8
	s_and_b32 s79, s34, 15
	s_lshl_b32 s79, s79, 7
	v_lshrrev_b32_e32 v128, 6, v218
	v_bfe_u32 v129, v218, 5, 1
	v_bfe_u32 v130, v218, 2, 1
	v_bfe_u32 v131, v218, 3, 2
	v_lshlrev_b32_e32 v132, 4, v128
	v_lshl_add_u32 v132, v129, 3, v132
	v_lshl_add_u32 v132, v130, 2, v132
	v_add_u32_e32 v132, v132, v131
	v_and_b32_e32 v133, 3, v218
	v_lshlrev_b32_e32 v133, 4, v133
	v_lshl_add_u32 v200, v132, 11, v133
	v_mul_u32_u24_e32 v134, 80, v132
	v_add_u32_e32 v202, v134, v133
	v_and_b32_e32 v135, 31, v218
	v_lshrrev_b32_e32 v136, 7, v218
	v_bfe_u32 v137, v218, 6, 1
	v_lshl_add_u32 v136, v136, 7, v135
	v_lshl_add_u32 v137, v137, 6, v135
	v_mul_u32_u24_e32 v136, 80, v136
	v_mul_u32_u24_e32 v137, 80, v137
	v_lshl_add_u32 v206, v129, 4, v136
	v_lshl_add_u32 v207, v129, 4, v137
	s_add_i32 s66, s78, 0
	s_lshl_b32 s66, s66, 11
	s_add_u32 s36, s6, s66
	s_addc_u32 s37, s7, 0
	s_add_i32 s66, s78, 64
	s_lshl_b32 s66, s66, 11
	s_add_u32 s38, s6, s66
	s_addc_u32 s39, s7, 0
	s_add_i32 s66, s78, 128
	s_lshl_b32 s66, s66, 11
	s_add_u32 s42, s6, s66
	s_addc_u32 s43, s7, 0
	s_add_i32 s66, s78, 192
	s_lshl_b32 s66, s66, 11
	s_add_u32 s46, s6, s66
	s_addc_u32 s47, s7, 0
	s_add_i32 s66, s79, 0
	s_lshl_b32 s66, s66, 11
	s_add_u32 s48, s0, s66
	s_addc_u32 s49, s1, 0
	s_add_i32 s66, s79, 64
	s_lshl_b32 s66, s66, 11
	s_add_u32 s50, s0, s66
	s_addc_u32 s51, s1, 0
	v_mov_b64_e32 v[0:1], 0
	v_mov_b64_e32 v[2:3], 0
	v_mov_b64_e32 v[4:5], 0
	v_mov_b64_e32 v[6:7], 0
	v_mov_b64_e32 v[8:9], 0
	v_mov_b64_e32 v[10:11], 0
	v_mov_b64_e32 v[12:13], 0
	v_mov_b64_e32 v[14:15], 0
	v_mov_b64_e32 v[16:17], 0
	v_mov_b64_e32 v[18:19], 0
	v_mov_b64_e32 v[20:21], 0
	v_mov_b64_e32 v[22:23], 0
	v_mov_b64_e32 v[24:25], 0
	v_mov_b64_e32 v[26:27], 0
	v_mov_b64_e32 v[28:29], 0
	v_mov_b64_e32 v[30:31], 0
	v_mov_b64_e32 v[32:33], 0
	v_mov_b64_e32 v[34:35], 0
	v_mov_b64_e32 v[36:37], 0
	v_mov_b64_e32 v[38:39], 0
	v_mov_b64_e32 v[40:41], 0
	v_mov_b64_e32 v[42:43], 0
	v_mov_b64_e32 v[44:45], 0
	v_mov_b64_e32 v[46:47], 0
	v_mov_b64_e32 v[48:49], 0
	v_mov_b64_e32 v[50:51], 0
	v_mov_b64_e32 v[52:53], 0
	v_mov_b64_e32 v[54:55], 0
	v_mov_b64_e32 v[56:57], 0
	v_mov_b64_e32 v[58:59], 0
	v_mov_b64_e32 v[60:61], 0
	v_mov_b64_e32 v[62:63], 0
	v_mov_b64_e32 v[64:65], 0
	v_mov_b64_e32 v[66:67], 0
	v_mov_b64_e32 v[68:69], 0
	v_mov_b64_e32 v[70:71], 0
	v_mov_b64_e32 v[72:73], 0
	v_mov_b64_e32 v[74:75], 0
	v_mov_b64_e32 v[76:77], 0
	v_mov_b64_e32 v[78:79], 0
	v_mov_b64_e32 v[80:81], 0
	v_mov_b64_e32 v[82:83], 0
	v_mov_b64_e32 v[84:85], 0
	v_mov_b64_e32 v[86:87], 0
	v_mov_b64_e32 v[88:89], 0
	v_mov_b64_e32 v[90:91], 0
	v_mov_b64_e32 v[92:93], 0
	v_mov_b64_e32 v[94:95], 0
	v_mov_b64_e32 v[96:97], 0
	v_mov_b64_e32 v[98:99], 0
	v_mov_b64_e32 v[100:101], 0
	v_mov_b64_e32 v[102:103], 0
	v_mov_b64_e32 v[104:105], 0
	v_mov_b64_e32 v[106:107], 0
	v_mov_b64_e32 v[108:109], 0
	v_mov_b64_e32 v[110:111], 0
	v_mov_b64_e32 v[112:113], 0
	v_mov_b64_e32 v[114:115], 0
	v_mov_b64_e32 v[116:117], 0
	v_mov_b64_e32 v[118:119], 0
	v_mov_b64_e32 v[120:121], 0
	v_mov_b64_e32 v[122:123], 0
	v_mov_b64_e32 v[124:125], 0
	v_mov_b64_e32 v[126:127], 0
	s_mov_b32 s64, 0
	v_add_u32_e32 v201, s64, v200
	global_load_dwordx4 v[128:131], v201, s[36:37]
	global_load_dwordx4 v[152:155], v201, s[36:37] offset:64
	global_load_dwordx4 v[132:135], v201, s[38:39]
	global_load_dwordx4 v[156:159], v201, s[38:39] offset:64
	global_load_dwordx4 v[136:139], v201, s[42:43]
	global_load_dwordx4 v[160:163], v201, s[42:43] offset:64
	global_load_dwordx4 v[140:143], v201, s[46:47]
	global_load_dwordx4 v[164:167], v201, s[46:47] offset:64
	global_load_dwordx4 v[144:147], v201, s[48:49]
	global_load_dwordx4 v[168:171], v201, s[48:49] offset:64
	global_load_dwordx4 v[148:151], v201, s[50:51]
	global_load_dwordx4 v[176:179], v201, s[50:51] offset:64
	s_movk_i32 s64, 0x80
	s_movk_i32 s65, 16
	s_waitcnt vmcnt(0)
	ds_write_b128 v202, v[128:131] offset:0
	ds_write_b128 v202, v[132:135] offset:5120
	ds_write_b128 v202, v[136:139] offset:10240
	ds_write_b128 v202, v[140:143] offset:15360
	ds_write_b128 v202, v[144:147] offset:40960
	ds_write_b128 v202, v[148:151] offset:46080
	s_waitcnt lgkmcnt(0)
	s_barrier
	ds_read_b128 v[196:199], v207 offset:40960
	ds_read_b128 v[228:231], v207 offset:43520
	ds_read_b128 v[180:183], v206 offset:0
	ds_read_b128 v[184:187], v206 offset:2560
	ds_read_b128 v[188:191], v206 offset:5120
	ds_read_b128 v[192:195], v206 offset:7680
; template <bool SWAP, int MI, class AF, class BF, class EF>
; DI void gemm_tile(const AF& af, const BF& bfn, const EF& ef, int m0, int n0, int K, char* smem) {
;     ...
;   for (int kt = 0; kt < nk; ++kt) {
;     const int cur = kt & 1;
;     const u16* Ab = As + cur * AROWS * 40;
;     const u16* Bb = Bs + cur * 128 * 40;
; #pragma unroll
;     for (int ks = 0; ks < 2; ++ks) {
;       bf16x8 a[MI], b[2];
; #pragma unroll
;       for (int i = 0; i < MI; ++i) a[i] = *(const bf16x8*)&Ab[(wm * (MI * 32) + i * 32 + l32) * 40 + ks * 16 + h * 8];
; #pragma unroll
;       for (int i = 0; i < 2; ++i) b[i] = *(const bf16x8*)&Bb[(wn * 64 + i * 32 + l32) * 40 + ks * 16 + h * 8];
; #pragma unroll
;       for (int i = 0; i < MI; ++i)
; #pragma unroll
;         for (int j = 0; j < 2; ++j)
;           acc[i][j] = SWAP ? __builtin_amdgcn_mfma_f32_32x32x16_bf16(b[j], a[i], acc[i][j], 0, 0, 0)
;                            : __builtin_amdgcn_mfma_f32_32x32x16_bf16(a[i], b[j], acc[i][j], 0, 0, 0);
;     }
;     {
;       u16* An = As + (cur ^ 1) * AROWS * 40;
;       u16* Bn = Bs + (cur ^ 1) * 128 * 40;
; #pragma unroll
;       for (int i = 0; i < MI; ++i) *(u32x4*)&An[(lrow + 64 * i) * 40 + lk] = ra[i];
; #pragma unroll
;       for (int i = 0; i < 2; ++i) *(u32x4*)&Bn[(lrow + 64 * i) * 40 + lk] = rb[i];
;       const int kn = (kt + 2 < nk) ? kt + 2 : nk - 1;
;       const int k0 = kn * 32 + lk;
; #pragma unroll
;       for (int i = 0; i < MI; ++i) ra[i] = *(const u32x4*)af(m0 + lrow + 64 * i, k0);
; #pragma unroll
;       for (int i = 0; i < 2; ++i) rb[i] = *(const u32x4*)bfn(n0 + lrow + 64 * i, k0);
;     }
;     __syncthreads();
;   }
.Lgemm_q_loop:
	ds_read_b128 v[232:235], v207 offset:40992
	ds_read_b128 v[236:239], v207 offset:43552
	ds_read_b128 v[220:223], v206 offset:32
	ds_read_b128 v[240:243], v206 offset:2592
	ds_read_b128 v[244:247], v206 offset:5152
	ds_read_b128 v[248:251], v206 offset:7712
	s_waitcnt lgkmcnt(9)
	v_mfma_f32_32x32x16_bf16 v[112:127], v[196:199], v[180:183], v[112:127]
	v_mfma_f32_32x32x16_bf16 v[96:111], v[228:231], v[180:183], v[96:111]
	s_waitcnt lgkmcnt(8)
	v_mfma_f32_32x32x16_bf16 v[80:95], v[196:199], v[184:187], v[80:95]
	v_mfma_f32_32x32x16_bf16 v[64:79], v[228:231], v[184:187], v[64:79]
	ds_write_b128 v202, v[152:155] offset:20480
	ds_write_b128 v202, v[156:159] offset:25600
	ds_write_b128 v202, v[160:163] offset:30720
	ds_write_b128 v202, v[164:167] offset:35840
	ds_write_b128 v202, v[168:171] offset:51200
	ds_write_b128 v202, v[176:179] offset:56320
	v_add_u32_e32 v201, s64, v200
	global_load_dwordx4 v[128:131], v201, s[36:37]
	global_load_dwordx4 v[152:155], v201, s[36:37] offset:64
	global_load_dwordx4 v[132:135], v201, s[38:39]
	global_load_dwordx4 v[156:159], v201, s[38:39] offset:64
	global_load_dwordx4 v[136:139], v201, s[42:43]
	global_load_dwordx4 v[160:163], v201, s[42:43] offset:64
	global_load_dwordx4 v[140:143], v201, s[46:47]
	global_load_dwordx4 v[164:167], v201, s[46:47] offset:64
	global_load_dwordx4 v[144:147], v201, s[48:49]
	global_load_dwordx4 v[168:171], v201, s[48:49] offset:64
	global_load_dwordx4 v[148:151], v201, s[50:51]
	global_load_dwordx4 v[176:179], v201, s[50:51] offset:64
	s_add_i32 s64, s64, 0x80
	s_min_u32 s64, s64, 0x780
	s_waitcnt lgkmcnt(13)
	v_mfma_f32_32x32x16_bf16 v[48:63], v[196:199], v[188:191], v[48:63]
	v_mfma_f32_32x32x16_bf16 v[32:47], v[228:231], v[188:191], v[32:47]
	s_waitcnt lgkmcnt(12)
	v_mfma_f32_32x32x16_bf16 v[16:31], v[196:199], v[192:195], v[16:31]
	v_mfma_f32_32x32x16_bf16 v[0:15], v[228:231], v[192:195], v[0:15]
	s_waitcnt lgkmcnt(0)
	s_barrier
	ds_read_b128 v[196:199], v207 offset:51200
	ds_read_b128 v[228:231], v207 offset:53760
	ds_read_b128 v[180:183], v206 offset:20480
	ds_read_b128 v[184:187], v206 offset:23040
	ds_read_b128 v[188:191], v206 offset:25600
	ds_read_b128 v[192:195], v206 offset:28160
	v_mfma_f32_32x32x16_bf16 v[112:127], v[232:235], v[220:223], v[112:127]
	v_mfma_f32_32x32x16_bf16 v[96:111], v[236:239], v[220:223], v[96:111]
	v_mfma_f32_32x32x16_bf16 v[80:95], v[232:235], v[240:243], v[80:95]
	v_mfma_f32_32x32x16_bf16 v[64:79], v[236:239], v[240:243], v[64:79]
	v_mfma_f32_32x32x16_bf16 v[48:63], v[232:235], v[244:247], v[48:63]
	v_mfma_f32_32x32x16_bf16 v[32:47], v[236:239], v[244:247], v[32:47]
	v_mfma_f32_32x32x16_bf16 v[16:31], v[232:235], v[248:251], v[16:31]
	v_mfma_f32_32x32x16_bf16 v[0:15], v[236:239], v[248:251], v[0:15]
	ds_read_b128 v[232:235], v207 offset:51232
	ds_read_b128 v[236:239], v207 offset:53792
	ds_read_b128 v[220:223], v206 offset:20512
	ds_read_b128 v[240:243], v206 offset:23072
	ds_read_b128 v[244:247], v206 offset:25632
	ds_read_b128 v[248:251], v206 offset:28192
	s_waitcnt lgkmcnt(9)
	v_mfma_f32_32x32x16_bf16 v[112:127], v[196:199], v[180:183], v[112:127]
	v_mfma_f32_32x32x16_bf16 v[96:111], v[228:231], v[180:183], v[96:111]
	s_waitcnt lgkmcnt(8)
	v_mfma_f32_32x32x16_bf16 v[80:95], v[196:199], v[184:187], v[80:95]
	v_mfma_f32_32x32x16_bf16 v[64:79], v[228:231], v[184:187], v[64:79]
	s_waitcnt vmcnt(0)
	ds_write_b128 v202, v[128:131] offset:0
	ds_write_b128 v202, v[132:135] offset:5120
	ds_write_b128 v202, v[136:139] offset:10240
	ds_write_b128 v202, v[140:143] offset:15360
	ds_write_b128 v202, v[144:147] offset:40960
	ds_write_b128 v202, v[148:151] offset:46080
	s_waitcnt lgkmcnt(13)
	v_mfma_f32_32x32x16_bf16 v[48:63], v[196:199], v[188:191], v[48:63]
	v_mfma_f32_32x32x16_bf16 v[32:47], v[228:231], v[188:191], v[32:47]
	s_waitcnt lgkmcnt(12)
	v_mfma_f32_32x32x16_bf16 v[16:31], v[196:199], v[192:195], v[16:31]
	v_mfma_f32_32x32x16_bf16 v[0:15], v[228:231], v[192:195], v[0:15]
	s_waitcnt lgkmcnt(0)
	s_barrier
	ds_read_b128 v[196:199], v207 offset:40960
	ds_read_b128 v[228:231], v207 offset:43520
	ds_read_b128 v[180:183], v206 offset:0
	ds_read_b128 v[184:187], v206 offset:2560
	ds_read_b128 v[188:191], v206 offset:5120
	ds_read_b128 v[192:195], v206 offset:7680
	v_mfma_f32_32x32x16_bf16 v[112:127], v[232:235], v[220:223], v[112:127]
	v_mfma_f32_32x32x16_bf16 v[96:111], v[236:239], v[220:223], v[96:111]
	v_mfma_f32_32x32x16_bf16 v[80:95], v[232:235], v[240:243], v[80:95]
	v_mfma_f32_32x32x16_bf16 v[64:79], v[236:239], v[240:243], v[64:79]
	v_mfma_f32_32x32x16_bf16 v[48:63], v[232:235], v[244:247], v[48:63]
	v_mfma_f32_32x32x16_bf16 v[32:47], v[236:239], v[244:247], v[32:47]
	v_mfma_f32_32x32x16_bf16 v[16:31], v[232:235], v[248:251], v[16:31]
	v_mfma_f32_32x32x16_bf16 v[0:15], v[236:239], v[248:251], v[0:15]
	s_add_i32 s65, s65, -1
	s_cmp_lg_u32 s65, 0
	s_cbranch_scc1 .Lgemm_q_loop
; DI u32 pack2(float a, float b) { return (u32)f2bf(a) | ((u32)f2bf(b) << 16); }
; template <bool SWAP, int MI, class AF, class BF, class EF>
; DI void gemm_tile(const AF& af, const BF& bfn, const EF& ef, int m0, int n0, int K, char* smem) {
;     ...
; #pragma unroll
;   for (int i = 0; i < MI; ++i)
; #pragma unroll
;     for (int j = 0; j < 2; ++j)
; #pragma unroll
;       for (int rg = 0; rg < 4; ++rg) {
;         const int m = SWAP ? (m0 + wm * (MI * 32) + i * 32 + l32) : (m0 + wm * (MI * 32) + i * 32 + rg * 8 + h * 4);
;         const int n = SWAP ? (n0 + wn * 64 + j * 32 + rg * 8 + h * 4) : (n0 + wn * 64 + j * 32 + l32);
;         ef(m, n, acc[i][j][rg * 4 + 0], acc[i][j][rg * 4 + 1], acc[i][j][rg * 4 + 2], acc[i][j][rg * 4 + 3]);
;       }
; DI void phase_q(const Params& p, int l, int bid, int nblk, char* smem) {
;     ...
;   auto ef = [=](int m, int n, float v0, float v1, float v2, float v3) {
;     const uint2 o = {pack2(v0, v1), pack2(v2, v3)};
;     *(uint2*)&Q[(size_t)m * 2048 + n] = o;
;   };
	s_waitcnt lgkmcnt(0)
	s_waitcnt vmcnt(0)
	v_and_b32_e32 v128, 31, v218
	v_lshrrev_b32_e32 v129, 7, v218
	v_bfe_u32 v130, v218, 5, 1
	v_bfe_u32 v131, v218, 6, 1
	v_lshl_add_u32 v128, v129, 7, v128
	v_mul_u32_u24_e32 v128, 272, v128
	v_lshlrev_b32_e32 v131, 7, v131
	v_lshl_add_u32 v131, v130, 3, v131
	v_add_u32_e32 v128, v128, v131
	s_nop 7
	v_cvt_pk_bf16_f32 v112, v112, v113
	v_cvt_pk_bf16_f32 v113, v114, v115
	v_cvt_pk_bf16_f32 v116, v116, v117
	v_cvt_pk_bf16_f32 v117, v118, v119
	v_cvt_pk_bf16_f32 v120, v120, v121
	v_cvt_pk_bf16_f32 v121, v122, v123
	v_cvt_pk_bf16_f32 v124, v124, v125
	v_cvt_pk_bf16_f32 v125, v126, v127
	ds_write_b64 v128, v[112:113] offset:0
	ds_write_b64 v128, v[116:117] offset:16
	ds_write_b64 v128, v[120:121] offset:32
	ds_write_b64 v128, v[124:125] offset:48
	v_cvt_pk_bf16_f32 v96, v96, v97
	v_cvt_pk_bf16_f32 v97, v98, v99
	v_cvt_pk_bf16_f32 v100, v100, v101
	v_cvt_pk_bf16_f32 v101, v102, v103
	v_cvt_pk_bf16_f32 v104, v104, v105
	v_cvt_pk_bf16_f32 v105, v106, v107
	v_cvt_pk_bf16_f32 v108, v108, v109
	v_cvt_pk_bf16_f32 v109, v110, v111
	ds_write_b64 v128, v[96:97] offset:64
	ds_write_b64 v128, v[100:101] offset:80
	ds_write_b64 v128, v[104:105] offset:96
	ds_write_b64 v128, v[108:109] offset:112
	v_cvt_pk_bf16_f32 v80, v80, v81
	v_cvt_pk_bf16_f32 v81, v82, v83
	v_cvt_pk_bf16_f32 v84, v84, v85
	v_cvt_pk_bf16_f32 v85, v86, v87
	v_cvt_pk_bf16_f32 v88, v88, v89
	v_cvt_pk_bf16_f32 v89, v90, v91
	v_cvt_pk_bf16_f32 v92, v92, v93
	v_cvt_pk_bf16_f32 v93, v94, v95
	ds_write_b64 v128, v[80:81] offset:8704
	ds_write_b64 v128, v[84:85] offset:8720
	ds_write_b64 v128, v[88:89] offset:8736
	ds_write_b64 v128, v[92:93] offset:8752
	v_cvt_pk_bf16_f32 v64, v64, v65
	v_cvt_pk_bf16_f32 v65, v66, v67
	v_cvt_pk_bf16_f32 v68, v68, v69
	v_cvt_pk_bf16_f32 v69, v70, v71
	v_cvt_pk_bf16_f32 v72, v72, v73
	v_cvt_pk_bf16_f32 v73, v74, v75
	v_cvt_pk_bf16_f32 v76, v76, v77
	v_cvt_pk_bf16_f32 v77, v78, v79
	ds_write_b64 v128, v[64:65] offset:8768
	ds_write_b64 v128, v[68:69] offset:8784
	ds_write_b64 v128, v[72:73] offset:8800
	ds_write_b64 v128, v[76:77] offset:8816
	v_cvt_pk_bf16_f32 v48, v48, v49
	v_cvt_pk_bf16_f32 v49, v50, v51
	v_cvt_pk_bf16_f32 v52, v52, v53
	v_cvt_pk_bf16_f32 v53, v54, v55
	v_cvt_pk_bf16_f32 v56, v56, v57
	v_cvt_pk_bf16_f32 v57, v58, v59
	v_cvt_pk_bf16_f32 v60, v60, v61
	v_cvt_pk_bf16_f32 v61, v62, v63
	ds_write_b64 v128, v[48:49] offset:17408
	ds_write_b64 v128, v[52:53] offset:17424
	ds_write_b64 v128, v[56:57] offset:17440
	ds_write_b64 v128, v[60:61] offset:17456
	v_cvt_pk_bf16_f32 v32, v32, v33
	v_cvt_pk_bf16_f32 v33, v34, v35
	v_cvt_pk_bf16_f32 v36, v36, v37
	v_cvt_pk_bf16_f32 v37, v38, v39
	v_cvt_pk_bf16_f32 v40, v40, v41
	v_cvt_pk_bf16_f32 v41, v42, v43
	v_cvt_pk_bf16_f32 v44, v44, v45
	v_cvt_pk_bf16_f32 v45, v46, v47
	ds_write_b64 v128, v[32:33] offset:17472
	ds_write_b64 v128, v[36:37] offset:17488
	ds_write_b64 v128, v[40:41] offset:17504
	ds_write_b64 v128, v[44:45] offset:17520
	v_cvt_pk_bf16_f32 v16, v16, v17
	v_cvt_pk_bf16_f32 v17, v18, v19
	v_cvt_pk_bf16_f32 v20, v20, v21
	v_cvt_pk_bf16_f32 v21, v22, v23
	v_cvt_pk_bf16_f32 v24, v24, v25
	v_cvt_pk_bf16_f32 v25, v26, v27
	v_cvt_pk_bf16_f32 v28, v28, v29
	v_cvt_pk_bf16_f32 v29, v30, v31
	ds_write_b64 v128, v[16:17] offset:26112
	ds_write_b64 v128, v[20:21] offset:26128
	ds_write_b64 v128, v[24:25] offset:26144
	ds_write_b64 v128, v[28:29] offset:26160
	v_cvt_pk_bf16_f32 v0, v0, v1
	v_cvt_pk_bf16_f32 v1, v2, v3
	v_cvt_pk_bf16_f32 v4, v4, v5
	v_cvt_pk_bf16_f32 v5, v6, v7
	v_cvt_pk_bf16_f32 v8, v8, v9
	v_cvt_pk_bf16_f32 v9, v10, v11
	v_cvt_pk_bf16_f32 v12, v12, v13
	v_cvt_pk_bf16_f32 v13, v14, v15
	ds_write_b64 v128, v[0:1] offset:26176
	ds_write_b64 v128, v[4:5] offset:26192
	ds_write_b64 v128, v[8:9] offset:26208
	ds_write_b64 v128, v[12:13] offset:26224
	s_lshl_b32 s16, s78, 12
	s_lshl_b32 s17, s79, 1
	s_add_u32 s16, s16, s17
	s_add_u32 s16, s96, s16
	s_addc_u32 s17, s97, 0
	s_movk_i32 s38, 0x1000
	s_mov_b32 s39, 0x10000
	v_lshrrev_b32_e32 v129, 4, v218
	v_and_b32_e32 v130, 15, v218
	v_mul_u32_u24_e32 v131, 272, v129
	v_mul_lo_u32 v132, v129, s38
	v_lshl_add_u32 v131, v130, 4, v131
	v_lshl_add_u32 v132, v130, 4, v132
	s_waitcnt lgkmcnt(0)
	s_barrier
	ds_read_b128 v[0:3], v131 offset:0
	ds_read_b128 v[4:7], v131 offset:4352
	ds_read_b128 v[8:11], v131 offset:8704
	ds_read_b128 v[12:15], v131 offset:13056
	ds_read_b128 v[16:19], v131 offset:17408
	ds_read_b128 v[20:23], v131 offset:21760
	ds_read_b128 v[24:27], v131 offset:26112
	ds_read_b128 v[28:31], v131 offset:30464
	ds_read_b128 v[32:35], v131 offset:34816
	ds_read_b128 v[36:39], v131 offset:39168
	ds_read_b128 v[40:43], v131 offset:43520
	ds_read_b128 v[44:47], v131 offset:47872
	ds_read_b128 v[48:51], v131 offset:52224
	ds_read_b128 v[52:55], v131 offset:56576
	ds_read_b128 v[56:59], v131 offset:60928
	ds_read_b128 v[60:63], v131 offset:65280
	s_waitcnt lgkmcnt(15)
	global_store_dwordx4 v132, v[0:3], s[16:17]
	s_add_u32 s16, s16, s39
	s_addc_u32 s17, s17, 0
	s_waitcnt lgkmcnt(14)
	global_store_dwordx4 v132, v[4:7], s[16:17]
	s_add_u32 s16, s16, s39
	s_addc_u32 s17, s17, 0
	s_waitcnt lgkmcnt(13)
	global_store_dwordx4 v132, v[8:11], s[16:17]
	s_add_u32 s16, s16, s39
	s_addc_u32 s17, s17, 0
	s_waitcnt lgkmcnt(12)
	global_store_dwordx4 v132, v[12:15], s[16:17]
	s_add_u32 s16, s16, s39
	s_addc_u32 s17, s17, 0
	s_waitcnt lgkmcnt(11)
	global_store_dwordx4 v132, v[16:19], s[16:17]
	s_add_u32 s16, s16, s39
	s_addc_u32 s17, s17, 0
	s_waitcnt lgkmcnt(10)
	global_store_dwordx4 v132, v[20:23], s[16:17]
	s_add_u32 s16, s16, s39
	s_addc_u32 s17, s17, 0
	s_waitcnt lgkmcnt(9)
	global_store_dwordx4 v132, v[24:27], s[16:17]
	s_add_u32 s16, s16, s39
	s_addc_u32 s17, s17, 0
	s_waitcnt lgkmcnt(8)
	global_store_dwordx4 v132, v[28:31], s[16:17]
	s_add_u32 s16, s16, s39
	s_addc_u32 s17, s17, 0
	s_waitcnt lgkmcnt(7)
	global_store_dwordx4 v132, v[32:35], s[16:17]
	s_add_u32 s16, s16, s39
	s_addc_u32 s17, s17, 0
	s_waitcnt lgkmcnt(6)
	global_store_dwordx4 v132, v[36:39], s[16:17]
	s_add_u32 s16, s16, s39
	s_addc_u32 s17, s17, 0
	s_waitcnt lgkmcnt(5)
	global_store_dwordx4 v132, v[40:43], s[16:17]
	s_add_u32 s16, s16, s39
	s_addc_u32 s17, s17, 0
	s_waitcnt lgkmcnt(4)
	global_store_dwordx4 v132, v[44:47], s[16:17]
	s_add_u32 s16, s16, s39
	s_addc_u32 s17, s17, 0
	s_waitcnt lgkmcnt(3)
	global_store_dwordx4 v132, v[48:51], s[16:17]
	s_add_u32 s16, s16, s39
	s_addc_u32 s17, s17, 0
	s_waitcnt lgkmcnt(2)
	global_store_dwordx4 v132, v[52:55], s[16:17]
	s_add_u32 s16, s16, s39
	s_addc_u32 s17, s17, 0
	s_waitcnt lgkmcnt(1)
	global_store_dwordx4 v132, v[56:59], s[16:17]
	s_add_u32 s16, s16, s39
	s_addc_u32 s17, s17, 0
	s_waitcnt lgkmcnt(0)
	global_store_dwordx4 v132, v[60:63], s[16:17]
	s_barrier
	s_add_i32 s34, s34, s54
	s_cmp_lt_i32 s34, s13
	s_cbranch_scc1 .LBB0_1387

; #define GBAR() xcd_barrier(bar)
; __global__ void __launch_bounds__(NTHR, 2) mega(Params p) {
;     ...
;   for (int l = 0; l < 2; ++l) {
;     for (int xs = 0; xs < EXTRA_SYNCS; ++xs) GBAR();
;     run_stage<0>(p, l, bid, nblk, smem); GBAR();
;     run_stage<1>(p, l, bid, nblk, smem); GBAR();
;     run_stage<2>(p, l, bid, nblk, smem); GBAR();
;     run_stage<3>(p, l, bid, nblk, smem); GBAR();
;     run_stage<4>(p, l, bid, nblk, smem); GBAR();
;     run_stage<5>(p, l, bid, nblk, smem); GBAR();
;     run_stage<6>(p, l, bid, nblk, smem); GBAR();
;     run_stage<7>(p, l, bid, nblk, smem); GBAR();
;     run_stage<8>(p, l, bid, nblk, smem); GBAR();
;     run_stage<9>(p, l, bid, nblk, smem);
;     if (l == 0) GBAR();
;   }
.Lpeer_norestore:
	s_waitcnt vmcnt(0) lgkmcnt(0)
	v_readlane_b32 s55, v254, 12
	v_readlane_b32 s0, v254, 8
	v_readlane_b32 s1, v254, 9
	s_mov_b64 s[70:71], -1
	s_andn2_b64 vcc, exec, s[0:1]
	s_mov_b64 s[0:1], -1
	s_cbranch_vccz .LBB0_1559
	s_getpc_b64 s[98:99]
